# v38 + GEMM K-loops software-pipelined across the barrier (fragments prefetched one step ahead, mid-step barrier + DMA, 3-slot LDS ring)
# baseline (speedup 1.0000x reference)
; template <int MODE, bool SWAP, int MT>
; DI void gemm_tile(const int wv_, const Params& p, const u16* __restrict__ A, const u16* __restrict__ Bt, int brow, int bcol, char* smem, const float* gnext) {
;     ...
;   const int tid = tid_, wid = tid >> 6, lane = tid & 63, wr = wid >> 1, wc = wid & 1, fr = lane & 15, fq = lane >> 4;
;   f32x4 acc[MT][4];
; #pragma unroll
;   for (int m = 0; m < MT; ++m)
; #pragma unroll
;     for (int n = 0; n < 4; ++n) acc[m][n] = f32x4{0.f, 0.f, 0.f, 0.f};
;   const int ra = tid >> 2, cb = (tid & 3) * 8;
;   const u16* ga0 = A + (size_t)(brow + ra) * 1024 + cb;
;   const u16* ga1 = A + (size_t)(brow + 128 + ra) * 1024 + cb;
;   const u16* gb0 = Bt + (size_t)(bcol + ra) * 1024 + cb;
;   auto stage = [&](int t, int buf) {
;     char* sA = smem + buf * 24576; char* sB = sA + 16384;
;     if (MT >= 2 || tid < 256) __builtin_amdgcn_global_load_lds((const unsigned*)(ga0 + t * 32), (unsigned*)(sA + tid * 16), 16, 0, 0);
;     if (MT == 4) __builtin_amdgcn_global_load_lds((const unsigned*)(ga1 + t * 32), (unsigned*)(sA + 8192 + tid * 16), 16, 0, 0);
;     __builtin_amdgcn_global_load_lds((const unsigned*)(gb0 + t * 32), (unsigned*)(sB + tid * 16), 16, 0, 0);
;   };
;   stage(0, 0);
.LBB0_84:
	s_mul_hi_i32 s0, s14, 0x92492493
	s_add_i32 s0, s0, s14
	s_lshr_b32 s1, s0, 31
	s_ashr_i32 s0, s0, 4
	s_add_i32 s19, s0, s1
	s_mul_i32 s0, s19, 0xffffffe4
	s_add_i32 s0, s0, s14
	s_and_b32 s1, s0, -4
	s_lshl_b32 s18, s19, 8
	s_lshl_b32 s15, s0, 7
	s_cmp_lg_u32 s1, 20
	s_mov_b64 s[0:1], -1
	s_mulk_i32 s19, 0xe00
	s_cbranch_scc0 .LBB0_88
	s_mov_b32 s1, 0
	v_readlane_b32 s20, v127, 0
	v_mbcnt_lo_u32_b32 v0, -1, s1
	v_mbcnt_hi_u32_b32 v0, -1, v0
	v_add_u32_e32 v12, s33, v0
	s_mov_b32 s1, s16
	v_ashrrev_i32_e32 v13, 2, v12
	v_add_u32_e32 v0, s18, v13
	s_mov_b32 s1, s17
	v_ashrrev_i32_e32 v1, 31, v0
	v_lshlrev_b64 v[4:5], 11, v[0:1]
	v_readlane_b32 s21, v127, 1
	v_lshlrev_b32_e32 v76, 4, v12
	v_and_b32_e32 v2, 48, v76
	v_lshl_add_u64 v[6:7], s[20:21], 0, v[4:5]
	v_add_u32_e32 v0, 0x80, v0
	v_readfirstlane_b32 s1, v76
	v_lshl_add_u64 v[6:7], v[6:7], 0, v[2:3]
	v_ashrrev_i32_e32 v1, 31, v0
	s_mov_b32 m0, s1
	v_lshlrev_b64 v[8:9], 11, v[0:1]
	global_load_lds_dwordx4 v[6:7], off
	v_add_u32_e32 v6, 0x2000, v76
	v_lshl_add_u64 v[0:1], s[20:21], 0, v[8:9]
	v_add_u32_e32 v10, s15, v13
	v_readfirstlane_b32 s1, v6
	v_lshl_add_u64 v[0:1], v[0:1], 0, v[2:3]
	v_ashrrev_i32_e32 v11, 31, v10
	s_mov_b32 m0, s1
	v_lshlrev_b64 v[10:11], 11, v[10:11]
	global_load_lds_dwordx4 v[0:1], off
	v_add_u32_e32 v0, 0x4000, v76
	v_lshl_add_u64 v[10:11], s[2:3], 0, v[10:11]
	v_readfirstlane_b32 s1, v0
	v_lshl_add_u64 v[10:11], v[10:11], 0, v[2:3]
	s_mov_b32 m0, s1
	v_and_b32_e32 v74, 15, v12
	global_load_lds_dwordx4 v[10:11], off
	v_readlane_b32 s20, v127, 22
	v_bfe_u32 v72, v12, 6, 1
	v_ashrrev_i32_e32 v73, 7, v12
	v_lshlrev_b32_e32 v0, 6, v74
	v_or_b32_e32 v4, v4, v2
	v_readlane_b32 s21, v127, 23
	v_lshl_or_b32 v78, v72, 12, v0
	v_lshl_or_b32 v79, v73, 12, v0
	v_lshl_add_u64 v[0:1], s[20:21], 0, v[4:5]
	v_add_u32_e32 v4, s12, v13
	v_subrev_u32_e32 v4, s19, v4
	v_ashrrev_i32_e32 v5, 31, v4
	v_lshlrev_b64 v[4:5], 11, v[4:5]
	v_or_b32_e32 v4, v4, v2
	v_bfe_u32 v75, v12, 4, 2
	v_or_b32_e32 v8, v8, v2
	v_lshl_add_u64 v[70:71], s[4:5], 0, v[4:5]
	v_mov_b32_e32 v4, 0
	s_mov_b32 s0, 0
	v_lshlrev_b32_e32 v77, 4, v75
	v_lshl_add_u64 v[68:69], s[20:21], 0, v[8:9]
	v_mov_b32_e32 v5, v4
	v_mov_b32_e32 v6, v4
	v_mov_b32_e32 v7, v4
	v_mov_b32_e32 v8, v4
	v_mov_b32_e32 v9, v4
	v_mov_b32_e32 v10, v4
	v_mov_b32_e32 v11, v4
	v_mov_b32_e32 v12, v4
	v_mov_b32_e32 v13, v4
	v_mov_b32_e32 v14, v4
	v_mov_b32_e32 v15, v4
	v_mov_b32_e32 v16, v4
	v_mov_b32_e32 v17, v4
	v_mov_b32_e32 v18, v4
	v_mov_b32_e32 v19, v4
	v_mov_b32_e32 v20, v4
	v_mov_b32_e32 v21, v4
	v_mov_b32_e32 v22, v4
	v_mov_b32_e32 v23, v4
	v_mov_b32_e32 v24, v4
	v_mov_b32_e32 v25, v4
	v_mov_b32_e32 v26, v4
	v_mov_b32_e32 v27, v4
	v_mov_b32_e32 v28, v4
	v_mov_b32_e32 v29, v4
	v_mov_b32_e32 v30, v4
	v_mov_b32_e32 v31, v4
	v_mov_b32_e32 v32, v4
	v_mov_b32_e32 v33, v4
	v_mov_b32_e32 v34, v4
	v_mov_b32_e32 v35, v4
	v_mov_b32_e32 v44, v4
	v_mov_b32_e32 v45, v4
	v_mov_b32_e32 v46, v4
	v_mov_b32_e32 v47, v4
	v_mov_b32_e32 v36, v4
	v_mov_b32_e32 v37, v4
	v_mov_b32_e32 v38, v4
	v_mov_b32_e32 v39, v4
	v_mov_b32_e32 v40, v4
	v_mov_b32_e32 v41, v4
	v_mov_b32_e32 v42, v4
	v_mov_b32_e32 v43, v4
	v_mov_b32_e32 v48, v4
	v_mov_b32_e32 v49, v4
	v_mov_b32_e32 v50, v4
	v_mov_b32_e32 v51, v4
	v_mov_b32_e32 v52, v4
	v_mov_b32_e32 v53, v4
	v_mov_b32_e32 v54, v4
	v_mov_b32_e32 v55, v4
	v_mov_b32_e32 v56, v4
	v_mov_b32_e32 v57, v4
	v_mov_b32_e32 v58, v4
	v_mov_b32_e32 v59, v4
	v_mov_b32_e32 v60, v4
	v_mov_b32_e32 v61, v4
	v_mov_b32_e32 v62, v4
	v_mov_b32_e32 v63, v4
	v_mov_b32_e32 v64, v4
	v_mov_b32_e32 v65, v4
	v_mov_b32_e32 v66, v4
	v_mov_b32_e32 v67, v4
	v_readlane_b32 s22, v127, 2
	v_readlane_b32 s23, v127, 3
	v_readfirstlane_b32 s98, v76
	s_movk_i32 s99, 0x6000
	s_add_i32 s101, s98, s99
	s_mov_b32 m0, s101
	s_add_i32 s101, s101, 0x2000
	global_load_lds_dwordx4 v[0:1], off
	s_mov_b32 m0, s101
	s_add_i32 s101, s101, 0x2000
	global_load_lds_dwordx4 v[68:69], off
	s_mov_b32 m0, s101
	s_add_i32 s99, s99, 0x6000
	global_load_lds_dwordx4 v[70:71], off
	s_cmp_eq_u32 s99, 0x12000
	s_cselect_b32 s99, 0, s99
	v_lshl_add_u64 v[0:1], v[0:1], 0, 64
	v_lshl_add_u64 v[68:69], v[68:69], 0, 64
	v_lshl_add_u64 v[70:71], v[70:71], 0, 64
	s_add_i32 s101, s98, s99
	s_mov_b32 m0, s101
	s_add_i32 s101, s101, 0x2000
	global_load_lds_dwordx4 v[0:1], off
	s_mov_b32 m0, s101
	s_add_i32 s101, s101, 0x2000
	global_load_lds_dwordx4 v[68:69], off
	s_mov_b32 m0, s101
	s_add_i32 s99, s99, 0x6000
	global_load_lds_dwordx4 v[70:71], off
	s_cmp_eq_u32 s99, 0x12000
	s_cselect_b32 s99, 0, s99
	v_lshl_add_u64 v[0:1], v[0:1], 0, 64
	v_lshl_add_u64 v[68:69], v[68:69], 0, 64
	v_lshl_add_u64 v[70:71], v[70:71], 0, 64
	s_mov_b32 s100, 0
	s_waitcnt vmcnt(6)
	s_barrier
	v_or_b32_e32 v112, s100, v77
	v_add_u32_e32 v113, v112, v78
	v_add_u32_e32 v112, v112, v79
	ds_read_b128 v[80:83], v113 offset:16384
	ds_read_b128 v[84:87], v113 offset:17408
	ds_read_b128 v[88:91], v113 offset:18432
	ds_read_b128 v[92:95], v113 offset:19456
	ds_read_b128 v[96:99], v112
	ds_read_b128 v[100:103], v112 offset:1024
	ds_read_b128 v[104:107], v112 offset:2048
	ds_read_b128 v[108:111], v112 offset:3072
	s_add_i32 s100, s100, 0x6000
	s_cmp_eq_u32 s100, 0x12000
	s_cselect_b32 s100, 0, s100
; DI float rowscale(const float* ss, int R) {
;   const float4* q = (const float4*)(ss + (size_t)R * 16);
;   float4 a = q[0], b = q[1], c = q[2], d = q[3];
;   float t = ((a.x + a.y) + (a.z + a.w)) + ((b.x + b.y) + (b.z + b.w)) + ((c.x + c.y) + (c.z + c.w)) + ((d.x + d.y) + (d.z + d.w));
;   return rsqrtf(t * (1.f / 1024.f) + 1e-6f);
; template <int MODE, bool SWAP, int MT>
; DI void gemm_tile(const int wv_, const Params& p, const u16* __restrict__ A, const u16* __restrict__ Bt, int brow, int bcol, char* smem, const float* gnext) {
;     ...
;   for (int t = 0; t < 32; ++t) {
;     asm volatile("s_waitcnt vmcnt(0)" ::: "memory");
;     __syncthreads();
;     if (t + 1 < 32) stage(t + 1, (t + 1) & 1);
;     const char* sA = smem + (t & 1) * 24576; const char* sB = sA + 16384;
;     bf16x8 Af[MT], Bf[4];
; #pragma unroll
;     for (int n = 0; n < 4; ++n) Bf[n] = *(const bf16x8*)(sB + (wc * 64 + n * 16 + fr) * 64 + fq * 16);
;     constexpr int MH = MT >= 2 ? MT / 2 : 1;
; #pragma unroll
;     for (int m = 0; m < MH; ++m) Af[m] = *(const bf16x8*)(sA + (wr * (16 * MT) + m * 16 + fr) * 64 + fq * 16);
;     __builtin_amdgcn_sched_barrier(0);
; #pragma unroll
;     for (int m = MH; m < MT; ++m) Af[m] = *(const bf16x8*)(sA + (wr * (16 * MT) + m * 16 + fr) * 64 + fq * 16);
; #pragma unroll
;     for (int m = 0; m < MH; ++m)
; #pragma unroll
;       for (int n = 0; n < 4; ++n)
;         acc[m][n] = SWAP ? __builtin_amdgcn_mfma_f32_16x16x32_bf16(Bf[n], Af[m], acc[m][n], 0, 0, 0)
;                          : __builtin_amdgcn_mfma_f32_16x16x32_bf16(Af[m], Bf[n], acc[m][n], 0, 0, 0);
;     __builtin_amdgcn_sched_barrier(0);
; #pragma unroll
;     for (int m = MH; m < MT; ++m)
; #pragma unroll
;       for (int n = 0; n < 4; ++n)
;         acc[m][n] = SWAP ? __builtin_amdgcn_mfma_f32_16x16x32_bf16(Bf[n], Af[m], acc[m][n], 0, 0, 0)
;                          : __builtin_amdgcn_mfma_f32_16x16x32_bf16(Af[m], Bf[n], acc[m][n], 0, 0, 0);
;   }
;   __syncthreads();
.LBB0_86:
	s_add_i32 s1, s0, 1
	s_waitcnt lgkmcnt(0)
	v_mfma_f32_16x16x32_bf16 v[64:67], v[80:83], v[96:99], v[64:67]
	v_mfma_f32_16x16x32_bf16 v[60:63], v[84:87], v[96:99], v[60:63]
	v_mfma_f32_16x16x32_bf16 v[56:59], v[88:91], v[96:99], v[56:59]
	v_mfma_f32_16x16x32_bf16 v[52:55], v[92:95], v[96:99], v[52:55]
	v_mfma_f32_16x16x32_bf16 v[48:51], v[80:83], v[100:103], v[48:51]
	v_mfma_f32_16x16x32_bf16 v[40:43], v[84:87], v[100:103], v[40:43]
	v_mfma_f32_16x16x32_bf16 v[36:39], v[88:91], v[100:103], v[36:39]
	v_mfma_f32_16x16x32_bf16 v[44:47], v[92:95], v[100:103], v[44:47]
	s_cmp_gt_u32 s0, 29
	s_cbranch_scc1 .Lpp_last_1
	s_waitcnt vmcnt(3)
	s_barrier
	s_cmp_gt_u32 s0, 28
	s_cbranch_scc1 .Lpp_nodma_1
	s_add_i32 s101, s98, s99
	s_mov_b32 m0, s101
	s_add_i32 s101, s101, 0x2000
	global_load_lds_dwordx4 v[0:1], off
	s_mov_b32 m0, s101
	s_add_i32 s101, s101, 0x2000
	global_load_lds_dwordx4 v[68:69], off
	s_mov_b32 m0, s101
	s_add_i32 s99, s99, 0x6000
	global_load_lds_dwordx4 v[70:71], off
	s_cmp_eq_u32 s99, 0x12000
	s_cselect_b32 s99, 0, s99
	v_lshl_add_u64 v[0:1], v[0:1], 0, 64
	v_lshl_add_u64 v[68:69], v[68:69], 0, 64
	v_lshl_add_u64 v[70:71], v[70:71], 0, 64
.Lpp_nodma_1:
	v_mfma_f32_16x16x32_bf16 v[32:35], v[80:83], v[104:107], v[32:35]
	v_mfma_f32_16x16x32_bf16 v[28:31], v[84:87], v[104:107], v[28:31]
	v_mfma_f32_16x16x32_bf16 v[24:27], v[88:91], v[104:107], v[24:27]
	v_mfma_f32_16x16x32_bf16 v[20:23], v[92:95], v[104:107], v[20:23]
	v_mfma_f32_16x16x32_bf16 v[16:19], v[80:83], v[108:111], v[16:19]
	v_mfma_f32_16x16x32_bf16 v[12:15], v[84:87], v[108:111], v[12:15]
	v_mfma_f32_16x16x32_bf16 v[8:11], v[88:91], v[108:111], v[8:11]
	v_mfma_f32_16x16x32_bf16 v[4:7], v[92:95], v[108:111], v[4:7]
	v_or_b32_e32 v112, s100, v77
	v_add_u32_e32 v113, v112, v78
	v_add_u32_e32 v112, v112, v79
	ds_read_b128 v[80:83], v113 offset:16384
	ds_read_b128 v[84:87], v113 offset:17408
	ds_read_b128 v[88:91], v113 offset:18432
	ds_read_b128 v[92:95], v113 offset:19456
	ds_read_b128 v[96:99], v112
	ds_read_b128 v[100:103], v112 offset:1024
	ds_read_b128 v[104:107], v112 offset:2048
	ds_read_b128 v[108:111], v112 offset:3072
	s_add_i32 s100, s100, 0x6000
	s_cmp_eq_u32 s100, 0x12000
	s_cselect_b32 s100, 0, s100
	s_mov_b32 s0, s1
	s_branch .LBB0_86
.Lpp_last_1:
	v_mfma_f32_16x16x32_bf16 v[32:35], v[80:83], v[104:107], v[32:35]
	v_mfma_f32_16x16x32_bf16 v[28:31], v[84:87], v[104:107], v[28:31]
	v_mfma_f32_16x16x32_bf16 v[24:27], v[88:91], v[104:107], v[24:27]
	v_mfma_f32_16x16x32_bf16 v[20:23], v[92:95], v[104:107], v[20:23]
	v_mfma_f32_16x16x32_bf16 v[16:19], v[80:83], v[108:111], v[16:19]
	v_mfma_f32_16x16x32_bf16 v[12:15], v[84:87], v[108:111], v[12:15]
	v_mfma_f32_16x16x32_bf16 v[8:11], v[88:91], v[108:111], v[8:11]
	v_mfma_f32_16x16x32_bf16 v[4:7], v[92:95], v[108:111], v[4:7]
	s_mov_b32 s0, s1
	v_add_u32_e32 v0, v77, v79
	v_add_u32_e32 v1, v77, v78
	s_waitcnt vmcnt(0)
	s_waitcnt vmcnt(0)
	s_barrier
	ds_read_b128 v[68:71], v0 offset:25600
	ds_read_b128 v[80:83], v0 offset:24576
	ds_read_b128 v[76:79], v1 offset:44032
	ds_read_b128 v[84:87], v1 offset:43008
	ds_read_b128 v[88:91], v1 offset:41984
	ds_read_b128 v[92:95], v1 offset:40960
	s_waitcnt lgkmcnt(0)
	v_mfma_f32_16x16x32_bf16 v[64:67], v[92:95], v[80:83], v[64:67]
	v_mfma_f32_16x16x32_bf16 v[60:63], v[88:91], v[80:83], v[60:63]
	v_mfma_f32_16x16x32_bf16 v[56:59], v[84:87], v[80:83], v[56:59]
	v_mfma_f32_16x16x32_bf16 v[52:55], v[76:79], v[80:83], v[52:55]
	ds_read_b128 v[80:83], v0 offset:26624
	ds_read_b128 v[96:99], v0 offset:27648
	v_mfma_f32_16x16x32_bf16 v[48:51], v[92:95], v[68:71], v[48:51]
	v_mfma_f32_16x16x32_bf16 v[40:43], v[88:91], v[68:71], v[40:43]
	v_mfma_f32_16x16x32_bf16 v[36:39], v[84:87], v[68:71], v[36:39]
	v_mfma_f32_16x16x32_bf16 v[44:47], v[76:79], v[68:71], v[44:47]
	v_or_b32_e32 v0, s18, v74
	v_lshl_add_u32 v68, v73, 6, v0
	v_lshlrev_b32_e32 v0, 6, v72
	v_lshlrev_b32_e32 v1, 2, v75
	v_ashrrev_i32_e32 v69, 31, v68
	v_or3_b32 v70, v0, v1, s15
	v_lshlrev_b64 v[0:1], 6, v[68:69]
	v_lshl_add_u64 v[0:1], s[90:91], 0, v[0:1]
	s_waitcnt lgkmcnt(1)
	v_mfma_f32_16x16x32_bf16 v[32:35], v[92:95], v[80:83], v[32:35]
	s_waitcnt lgkmcnt(0)
	s_barrier
	v_mfma_f32_16x16x32_bf16 v[28:31], v[88:91], v[80:83], v[28:31]
	v_mov_b32_e32 v69, 0x358637bd
	v_ashrrev_i32_e32 v71, 31, v70
	v_mfma_f32_16x16x32_bf16 v[24:27], v[84:87], v[80:83], v[24:27]
	v_mfma_f32_16x16x32_bf16 v[20:23], v[76:79], v[80:83], v[20:23]
	v_mfma_f32_16x16x32_bf16 v[8:11], v[84:87], v[96:99], v[8:11]
	v_mfma_f32_16x16x32_bf16 v[4:7], v[76:79], v[96:99], v[4:7]
	global_load_dwordx4 v[72:75], v[0:1], off offset:32
	global_load_dwordx4 v[76:79], v[0:1], off offset:16
	global_load_dwordx4 v[80:83], v[0:1], off
	global_load_dwordx4 v[84:87], v[0:1], off offset:48
	s_waitcnt vmcnt(3)
	v_mov_b32_e32 v2, v73
	v_mfma_f32_16x16x32_bf16 v[12:15], v[88:91], v[96:99], v[12:15]
	s_waitcnt vmcnt(1)
	v_mov_b32_e32 v0, v81
	v_mov_b32_e32 v1, v82
	v_mov_b32_e32 v88, v77
	v_mov_b32_e32 v89, v78
	v_mov_b32_e32 v81, v83
	v_mov_b32_e32 v77, v79
	v_pk_add_f32 v[0:1], v[0:1], v[80:81]
	v_pk_add_f32 v[76:77], v[88:89], v[76:77]
	v_pk_add_f32 v[72:73], v[72:73], v[2:3]
	v_mov_b32_e32 v2, v75
	v_pk_add_f32 v[0:1], v[0:1], v[0:1] op_sel:[0,1] op_sel_hi:[1,0]
	v_pk_add_f32 v[76:77], v[76:77], v[76:77] op_sel:[0,1] op_sel_hi:[1,0]
	v_pk_add_f32 v[74:75], v[74:75], v[2:3]
	s_waitcnt vmcnt(0)
; DI unsigned pack2(float a, float b) { f32x2_t v = {a, b}; return __builtin_bit_cast(unsigned, __builtin_convertvector(v, bf16x2_t)); }
; DI float rowscale(const float* ss, int R) {
;   const float4* q = (const float4*)(ss + (size_t)R * 16);
;   float4 a = q[0], b = q[1], c = q[2], d = q[3];
;   float t = ((a.x + a.y) + (a.z + a.w)) + ((b.x + b.y) + (b.z + b.w)) + ((c.x + c.y) + (c.z + c.w)) + ((d.x + d.y) + (d.z + d.w));
;   return rsqrtf(t * (1.f / 1024.f) + 1e-6f);
; }
; template <int MODE, bool SWAP, int MT>
; DI void gemm_tile(const int wv_, const Params& p, const u16* __restrict__ A, const u16* __restrict__ Bt, int brow, int bcol, char* smem, const float* gnext) {
;     ...
;         const float rs = rowscale(p.ss, R);
; #pragma unroll
;         for (int n = 0; n < 4; ++n) { acc[m][n][0] *= rs; acc[m][n][1] *= rs; acc[m][n][2] *= rs; acc[m][n][3] *= rs; }
;         if (MODE == 0 && bcol >= 512 && bcol < 1536) {
;           int b = R / P, pos = R - b * P;
;           u16* dstb = (bcol < 1024 ? p.kc : p.vc);
; #pragma unroll
;           for (int n = 0; n < 4; ++n) {
;             int cc = (bcol & 511) + wc * 64 + n * 16 + fq * 4;
;             uint2 o; o.x = pack2(acc[m][n][0], acc[m][n][1]); o.y = pack2(acc[m][n][2], acc[m][n][3]);
;             *(uint2*)(dstb + ((size_t)((b * 8 + (cc >> 6)) * P + pos)) * 64 + (cc & 63)) = o;
;           }
;         } else {
;           const int LD = MODE == 0 ? LD_AB : LD_CD;
;           u16* pr = p.proj + (size_t)R * LD;
; #pragma unroll
;           for (int n = 0; n < 4; ++n) {
;             int col = bcol + wc * 64 + n * 16 + fq * 4;
;             if (MODE == 1 || col < 4184) {
;               uint2 o; o.x = pack2(acc[m][n][0], acc[m][n][1]); o.y = pack2(acc[m][n][2], acc[m][n][3]);
;               int pcol = (MODE == 0 && col >= 1536) ? col - 1024 : col;
;               *(uint2*)(pr + pcol) = o;
	v_mov_b32_e32 v1, v84
	v_mov_b32_e32 v77, v85
	v_mov_b32_e32 v73, v86
	v_mov_b32_e32 v75, v87
	v_pk_add_f32 v[0:1], v[0:1], v[76:77]
	v_pk_add_f32 v[72:73], v[72:73], v[74:75]
	v_mfma_f32_16x16x32_bf16 v[16:19], v[92:95], v[96:99], v[16:19]
	v_add_f32_e64 v0, v0, v72
	v_add_f32_e64 v1, v1, v73
	v_add_f32_e32 v0, v0, v1
	v_fmamk_f32 v0, v0, 0x3a800000, v69
	v_cmp_gt_f32_e32 vcc, s96, v0
	v_mul_f32_e32 v1, 0x4b800000, v0
	s_nop 0
	v_cndmask_b32_e32 v0, v0, v1, vcc
	v_rsq_f32_e32 v0, v0
	s_nop 0
	v_mul_f32_e32 v1, 0x45800000, v0
	v_cndmask_b32_e32 v0, v0, v1, vcc
	v_pk_mul_f32 v[72:73], v[64:65], v[0:1] op_sel_hi:[1,0]
	v_pk_mul_f32 v[66:67], v[66:67], v[0:1] op_sel_hi:[1,0]
	v_pk_mul_f32 v[64:65], v[60:61], v[0:1] op_sel_hi:[1,0]
	v_pk_mul_f32 v[62:63], v[62:63], v[0:1] op_sel_hi:[1,0]
	v_pk_mul_f32 v[60:61], v[56:57], v[0:1] op_sel_hi:[1,0]
	v_pk_mul_f32 v[58:59], v[58:59], v[0:1] op_sel_hi:[1,0]
	v_pk_mul_f32 v[56:57], v[52:53], v[0:1] op_sel_hi:[1,0]
	v_pk_mul_f32 v[54:55], v[54:55], v[0:1] op_sel_hi:[1,0]
	v_mov_b64_e32 v[0:1], s[68:69]
	v_mad_i64_i32 v[74:75], s[0:1], v68, s34, v[0:1]
	v_lshlrev_b64 v[52:53], 1, v[70:71]
	v_cvt_pk_bf16_f32 v56, v56, v57
	v_cvt_pk_bf16_f32 v57, v54, v55
	v_or_b32_e32 v54, 16, v68
	v_cvt_pk_bf16_f32 v72, v72, v73
	v_cvt_pk_bf16_f32 v73, v66, v67
	v_lshl_add_u64 v[66:67], v[74:75], 0, v[52:53]
	v_ashrrev_i32_e32 v55, 31, v54
	v_cvt_pk_bf16_f32 v64, v64, v65
	v_cvt_pk_bf16_f32 v65, v62, v63
	v_cvt_pk_bf16_f32 v60, v60, v61
	v_cvt_pk_bf16_f32 v61, v58, v59
	global_store_dwordx2 v[66:67], v[56:57], off offset:96
	v_lshlrev_b64 v[56:57], 6, v[54:55]
	global_store_dwordx2 v[66:67], v[72:73], off
	global_store_dwordx2 v[66:67], v[64:65], off offset:32
	global_store_dwordx2 v[66:67], v[60:61], off offset:64
	v_lshl_add_u64 v[70:71], s[90:91], 0, v[56:57]
	global_load_dwordx4 v[56:59], v[70:71], off offset:32
	global_load_dwordx4 v[60:63], v[70:71], off offset:16
	global_load_dwordx4 v[64:67], v[70:71], off
	s_nop 0
	global_load_dwordx4 v[70:73], v[70:71], off offset:48
	s_waitcnt vmcnt(3)
	v_mov_b32_e32 v2, v57
	s_waitcnt vmcnt(2)
	v_mov_b32_e32 v76, v61
	s_waitcnt vmcnt(1)
	v_mov_b32_e32 v74, v65
	v_mov_b32_e32 v75, v66
	v_mov_b32_e32 v77, v62
	v_mov_b32_e32 v65, v67
	v_mov_b32_e32 v61, v63
	v_pk_add_f32 v[64:65], v[74:75], v[64:65]
	v_pk_add_f32 v[60:61], v[76:77], v[60:61]
	v_pk_add_f32 v[56:57], v[56:57], v[2:3]
	v_mov_b32_e32 v2, v59
	v_pk_add_f32 v[64:65], v[64:65], v[64:65] op_sel:[0,1] op_sel_hi:[1,0]
	v_pk_add_f32 v[60:61], v[60:61], v[60:61] op_sel:[0,1] op_sel_hi:[1,0]
	v_pk_add_f32 v[58:59], v[58:59], v[2:3]
	s_waitcnt vmcnt(0)
	v_mov_b32_e32 v65, v70
	v_mov_b32_e32 v61, v71
	v_mov_b32_e32 v57, v72
	v_mov_b32_e32 v59, v73
	v_pk_add_f32 v[60:61], v[64:65], v[60:61]
	v_pk_add_f32 v[56:57], v[56:57], v[58:59]
	s_nop 0
	v_pk_add_f32 v[56:57], v[60:61], v[56:57]
	s_nop 0
	v_add_f32_e32 v2, v56, v57
	v_fmamk_f32 v2, v2, 0x3a800000, v69
	v_cmp_gt_f32_e32 vcc, s96, v2
	v_mul_f32_e32 v55, 0x4b800000, v2
	s_nop 0
	v_cndmask_b32_e32 v2, v2, v55, vcc
	v_rsq_f32_e32 v2, v2
	s_nop 0
	v_mul_f32_e32 v55, 0x45800000, v2
	v_cndmask_b32_e32 v2, v2, v55, vcc
	v_pk_mul_f32 v[48:49], v[48:49], v[2:3] op_sel_hi:[1,0]
	v_pk_mul_f32 v[50:51], v[50:51], v[2:3] op_sel_hi:[1,0]
	v_pk_mul_f32 v[36:37], v[36:37], v[2:3] op_sel_hi:[1,0]
	v_pk_mul_f32 v[38:39], v[38:39], v[2:3] op_sel_hi:[1,0]
	v_mad_i64_i32 v[54:55], s[0:1], v54, s34, v[0:1]
	v_pk_mul_f32 v[44:45], v[44:45], v[2:3] op_sel_hi:[1,0]
	v_cvt_pk_bf16_f32 v48, v48, v49
	v_cvt_pk_bf16_f32 v49, v50, v51
	v_lshl_add_u64 v[50:51], v[54:55], 0, v[52:53]
	v_cvt_pk_bf16_f32 v36, v36, v37
	v_cvt_pk_bf16_f32 v37, v38, v39
	v_pk_mul_f32 v[46:47], v[46:47], v[2:3] op_sel_hi:[1,0]
	global_store_dwordx2 v[50:51], v[36:37], off offset:64
	v_cvt_pk_bf16_f32 v36, v44, v45
	v_or_b32_e32 v44, 32, v68
	v_pk_mul_f32 v[40:41], v[40:41], v[2:3] op_sel_hi:[1,0]
	v_pk_mul_f32 v[42:43], v[42:43], v[2:3] op_sel_hi:[1,0]
	v_cvt_pk_bf16_f32 v37, v46, v47
	v_ashrrev_i32_e32 v45, 31, v44
	v_cvt_pk_bf16_f32 v40, v40, v41
	v_cvt_pk_bf16_f32 v41, v42, v43
	global_store_dwordx2 v[50:51], v[36:37], off offset:96
	v_lshlrev_b64 v[36:37], 6, v[44:45]
	global_store_dwordx2 v[50:51], v[48:49], off
	global_store_dwordx2 v[50:51], v[40:41], off offset:32
	v_lshl_add_u64 v[50:51], s[90:91], 0, v[36:37]
	global_load_dwordx4 v[36:39], v[50:51], off offset:32
	global_load_dwordx4 v[40:43], v[50:51], off offset:16
	global_load_dwordx4 v[46:49], v[50:51], off
	global_load_dwordx4 v[54:57], v[50:51], off offset:48
	s_waitcnt vmcnt(3)
	v_mov_b32_e32 v2, v37
	s_waitcnt vmcnt(2)
	v_mov_b32_e32 v58, v41
	s_waitcnt vmcnt(1)
	v_mov_b32_e32 v50, v47
	v_mov_b32_e32 v51, v48
	v_mov_b32_e32 v59, v42
	v_mov_b32_e32 v47, v49
	v_mov_b32_e32 v41, v43
	v_pk_add_f32 v[46:47], v[50:51], v[46:47]
	v_pk_add_f32 v[40:41], v[58:59], v[40:41]
	v_pk_add_f32 v[36:37], v[36:37], v[2:3]
	v_mov_b32_e32 v2, v39
	v_pk_add_f32 v[46:47], v[46:47], v[46:47] op_sel:[0,1] op_sel_hi:[1,0]
	v_pk_add_f32 v[40:41], v[40:41], v[40:41] op_sel:[0,1] op_sel_hi:[1,0]
	v_pk_add_f32 v[38:39], v[38:39], v[2:3]
	s_waitcnt vmcnt(0)
; DI unsigned pack2(float a, float b) { f32x2_t v = {a, b}; return __builtin_bit_cast(unsigned, __builtin_convertvector(v, bf16x2_t)); }
; template <int MODE, bool SWAP, int MT>
; DI void gemm_tile(const int wv_, const Params& p, const u16* __restrict__ A, const u16* __restrict__ Bt, int brow, int bcol, char* smem, const float* gnext) {
;     ...
;   const int ra = tid >> 2, cb = (tid & 3) * 8;
;   const u16* ga0 = A + (size_t)(brow + ra) * 1024 + cb;
;   const u16* ga1 = A + (size_t)(brow + 128 + ra) * 1024 + cb;
;   const u16* gb0 = Bt + (size_t)(bcol + ra) * 1024 + cb;
;   auto stage = [&](int t, int buf) {
;     char* sA = smem + buf * 24576; char* sB = sA + 16384;
;     if (MT >= 2 || tid < 256) __builtin_amdgcn_global_load_lds((const unsigned*)(ga0 + t * 32), (unsigned*)(sA + tid * 16), 16, 0, 0);
;     if (MT == 4) __builtin_amdgcn_global_load_lds((const unsigned*)(ga1 + t * 32), (unsigned*)(sA + 8192 + tid * 16), 16, 0, 0);
;     __builtin_amdgcn_global_load_lds((const unsigned*)(gb0 + t * 32), (unsigned*)(sB + tid * 16), 16, 0, 0);
;   };
;   stage(0, 0);
;     ...
;         const float rs = rowscale(p.ss, R);
; #pragma unroll
;         for (int n = 0; n < 4; ++n) { acc[m][n][0] *= rs; acc[m][n][1] *= rs; acc[m][n][2] *= rs; acc[m][n][3] *= rs; }
;         if (MODE == 0 && bcol >= 512 && bcol < 1536) {
;           int b = R / P, pos = R - b * P;
;           u16* dstb = (bcol < 1024 ? p.kc : p.vc);
; #pragma unroll
;           for (int n = 0; n < 4; ++n) {
;             int cc = (bcol & 511) + wc * 64 + n * 16 + fq * 4;
;             uint2 o; o.x = pack2(acc[m][n][0], acc[m][n][1]); o.y = pack2(acc[m][n][2], acc[m][n][3]);
;             *(uint2*)(dstb + ((size_t)((b * 8 + (cc >> 6)) * P + pos)) * 64 + (cc & 63)) = o;
;           }
;         } else {
;           const int LD = MODE == 0 ? LD_AB : LD_CD;
;           u16* pr = p.proj + (size_t)R * LD;
; #pragma unroll
;           for (int n = 0; n < 4; ++n) {
;             int col = bcol + wc * 64 + n * 16 + fq * 4;
;             if (MODE == 1 || col < 4184) {
;               uint2 o; o.x = pack2(acc[m][n][0], acc[m][n][1]); o.y = pack2(acc[m][n][2], acc[m][n][3]);
;               int pcol = (MODE == 0 && col >= 1536) ? col - 1024 : col;
;               *(uint2*)(pr + pcol) = o;
	v_mov_b32_e32 v47, v54
	v_mov_b32_e32 v41, v55
	v_mov_b32_e32 v37, v56
	v_mov_b32_e32 v39, v57
	v_pk_add_f32 v[40:41], v[46:47], v[40:41]
	v_pk_add_f32 v[36:37], v[36:37], v[38:39]
	s_nop 0
	v_pk_add_f32 v[36:37], v[40:41], v[36:37]
	s_nop 0
	v_add_f32_e32 v2, v36, v37
	v_fmamk_f32 v2, v2, 0x3a800000, v69
	v_cmp_gt_f32_e32 vcc, s96, v2
	v_mul_f32_e32 v36, 0x4b800000, v2
	s_nop 0
	v_cndmask_b32_e32 v2, v2, v36, vcc
	v_rsq_f32_e32 v2, v2
	s_nop 0
	v_mul_f32_e32 v36, 0x45800000, v2
	v_cndmask_b32_e32 v2, v2, v36, vcc
	v_pk_mul_f32 v[32:33], v[32:33], v[2:3] op_sel_hi:[1,0]
	v_pk_mul_f32 v[34:35], v[34:35], v[2:3] op_sel_hi:[1,0]
	v_pk_mul_f32 v[28:29], v[28:29], v[2:3] op_sel_hi:[1,0]
	v_pk_mul_f32 v[30:31], v[30:31], v[2:3] op_sel_hi:[1,0]
	v_mad_i64_i32 v[36:37], s[0:1], v44, s34, v[0:1]
	v_cvt_pk_bf16_f32 v32, v32, v33
	v_cvt_pk_bf16_f32 v33, v34, v35
	v_lshl_add_u64 v[34:35], v[36:37], 0, v[52:53]
	v_cvt_pk_bf16_f32 v28, v28, v29
	v_cvt_pk_bf16_f32 v29, v30, v31
	v_pk_mul_f32 v[20:21], v[20:21], v[2:3] op_sel_hi:[1,0]
	v_pk_mul_f32 v[22:23], v[22:23], v[2:3] op_sel_hi:[1,0]
	global_store_dwordx2 v[34:35], v[28:29], off offset:32
	v_or_b32_e32 v28, 48, v68
	v_pk_mul_f32 v[24:25], v[24:25], v[2:3] op_sel_hi:[1,0]
	v_pk_mul_f32 v[26:27], v[26:27], v[2:3] op_sel_hi:[1,0]
	v_cvt_pk_bf16_f32 v20, v20, v21
	v_cvt_pk_bf16_f32 v21, v22, v23
	v_ashrrev_i32_e32 v29, 31, v28
	v_cvt_pk_bf16_f32 v24, v24, v25
	v_cvt_pk_bf16_f32 v25, v26, v27
	global_store_dwordx2 v[34:35], v[20:21], off offset:96
	v_lshlrev_b64 v[20:21], 6, v[28:29]
	global_store_dwordx2 v[34:35], v[32:33], off
	global_store_dwordx2 v[34:35], v[24:25], off offset:64
	v_lshl_add_u64 v[34:35], s[90:91], 0, v[20:21]
	global_load_dwordx4 v[20:23], v[34:35], off offset:32
	global_load_dwordx4 v[24:27], v[34:35], off offset:16
	global_load_dwordx4 v[30:33], v[34:35], off
	s_nop 0
	global_load_dwordx4 v[34:37], v[34:35], off offset:48
	v_mad_i64_i32 v[0:1], s[0:1], v28, s34, v[0:1]
	v_lshl_add_u64 v[0:1], v[0:1], 0, v[52:53]
	s_mov_b64 s[0:1], 0x60
	s_waitcnt vmcnt(3)
	v_mov_b32_e32 v2, v21
	s_waitcnt vmcnt(2)
	v_mov_b32_e32 v40, v25
	s_waitcnt vmcnt(1)
	v_mov_b32_e32 v38, v31
	v_mov_b32_e32 v39, v32
	v_mov_b32_e32 v41, v26
	v_mov_b32_e32 v31, v33
	v_mov_b32_e32 v25, v27
	v_pk_add_f32 v[30:31], v[38:39], v[30:31]
	v_pk_add_f32 v[24:25], v[40:41], v[24:25]
	v_pk_add_f32 v[20:21], v[20:21], v[2:3]
	v_mov_b32_e32 v2, v23
	v_pk_add_f32 v[30:31], v[30:31], v[30:31] op_sel:[0,1] op_sel_hi:[1,0]
	v_pk_add_f32 v[24:25], v[24:25], v[24:25] op_sel:[0,1] op_sel_hi:[1,0]
	v_pk_add_f32 v[22:23], v[22:23], v[2:3]
	s_waitcnt vmcnt(0)
	v_mov_b32_e32 v31, v34
	v_mov_b32_e32 v25, v35
	v_mov_b32_e32 v21, v36
	v_mov_b32_e32 v23, v37
	v_pk_add_f32 v[24:25], v[30:31], v[24:25]
	v_pk_add_f32 v[20:21], v[20:21], v[22:23]
	s_nop 0
	v_pk_add_f32 v[20:21], v[24:25], v[20:21]
	s_nop 0
	v_add_f32_e32 v2, v20, v21
	v_fmamk_f32 v2, v2, 0x3a800000, v69
	v_cmp_gt_f32_e32 vcc, s96, v2
	v_mul_f32_e32 v20, 0x4b800000, v2
	s_nop 0
	v_cndmask_b32_e32 v2, v2, v20, vcc
	v_rsq_f32_e32 v2, v2
	s_nop 0
	v_mul_f32_e32 v20, 0x45800000, v2
	v_cndmask_b32_e32 v2, v2, v20, vcc
	v_pk_mul_f32 v[16:17], v[16:17], v[2:3] op_sel_hi:[1,0]
	v_pk_mul_f32 v[18:19], v[18:19], v[2:3] op_sel_hi:[1,0]
	v_pk_mul_f32 v[12:13], v[12:13], v[2:3] op_sel_hi:[1,0]
	v_pk_mul_f32 v[14:15], v[14:15], v[2:3] op_sel_hi:[1,0]
	v_pk_mul_f32 v[20:21], v[4:5], v[2:3] op_sel_hi:[1,0]
	v_pk_mul_f32 v[4:5], v[6:7], v[2:3] op_sel_hi:[1,0]
	v_cvt_pk_bf16_f32 v6, v16, v17
	v_cvt_pk_bf16_f32 v7, v18, v19
	v_pk_mul_f32 v[8:9], v[8:9], v[2:3] op_sel_hi:[1,0]
	v_pk_mul_f32 v[10:11], v[10:11], v[2:3] op_sel_hi:[1,0]
	global_store_dwordx2 v[0:1], v[6:7], off
	v_cvt_pk_bf16_f32 v6, v12, v13
	v_cvt_pk_bf16_f32 v7, v14, v15
	global_store_dwordx2 v[0:1], v[6:7], off offset:32
	v_cvt_pk_bf16_f32 v6, v8, v9
	v_cvt_pk_bf16_f32 v7, v10, v11
	global_store_dwordx2 v[0:1], v[6:7], off offset:64
	v_cvt_pk_bf16_f32 v2, v20, v21
	v_lshl_add_u64 v[6:7], v[0:1], 0, s[0:1]
	s_mov_b64 s[0:1], 0
	global_store_dword v[0:1], v2, off offset:96
.LBB0_88:
	s_and_b64 vcc, exec, s[0:1]
	s_cbranch_vccz .LBB0_83
	s_mov_b32 s1, 0
	v_readlane_b32 s20, v127, 0
	v_mbcnt_lo_u32_b32 v0, -1, s1
	v_mbcnt_hi_u32_b32 v0, -1, v0
	v_add_u32_e32 v12, s33, v0
	s_mov_b32 s1, s16
	v_ashrrev_i32_e32 v13, 2, v12
	v_add_u32_e32 v0, s18, v13
	s_mov_b32 s1, s17
	v_ashrrev_i32_e32 v1, 31, v0
	v_lshlrev_b64 v[4:5], 11, v[0:1]
	v_readlane_b32 s21, v127, 1
	v_lshlrev_b32_e32 v76, 4, v12
	v_and_b32_e32 v2, 48, v76
	v_lshl_add_u64 v[6:7], s[20:21], 0, v[4:5]
	v_add_u32_e32 v0, 0x80, v0
	v_readfirstlane_b32 s1, v76
	v_lshl_add_u64 v[6:7], v[6:7], 0, v[2:3]
	v_ashrrev_i32_e32 v1, 31, v0
	s_mov_b32 m0, s1
	v_lshlrev_b64 v[8:9], 11, v[0:1]
	global_load_lds_dwordx4 v[6:7], off
	v_add_u32_e32 v6, 0x2000, v76
	v_lshl_add_u64 v[0:1], s[20:21], 0, v[8:9]
	v_add_u32_e32 v10, s15, v13
	v_readfirstlane_b32 s1, v6
	v_lshl_add_u64 v[0:1], v[0:1], 0, v[2:3]
	v_ashrrev_i32_e32 v11, 31, v10
	s_mov_b32 m0, s1
	v_lshlrev_b64 v[10:11], 11, v[10:11]
	global_load_lds_dwordx4 v[0:1], off
	v_add_u32_e32 v0, 0x4000, v76
	v_lshl_add_u64 v[10:11], s[2:3], 0, v[10:11]
	v_readfirstlane_b32 s1, v0
	v_lshl_add_u64 v[10:11], v[10:11], 0, v[2:3]
	s_mov_b32 m0, s1
	v_and_b32_e32 v73, 15, v12
	global_load_lds_dwordx4 v[10:11], off
	v_readlane_b32 s20, v127, 22
	v_bfe_u32 v72, v12, 6, 1
	v_ashrrev_i32_e32 v74, 7, v12
	v_lshlrev_b32_e32 v0, 6, v73
	v_or_b32_e32 v4, v4, v2
	v_readlane_b32 s21, v127, 23
	v_lshl_or_b32 v78, v72, 12, v0
	v_lshl_or_b32 v79, v74, 12, v0
	v_lshl_add_u64 v[0:1], s[20:21], 0, v[4:5]
	v_add_u32_e32 v4, s12, v13
	v_subrev_u32_e32 v4, s19, v4
; template <int MODE, bool SWAP, int MT>
; DI void gemm_tile(const int wv_, const Params& p, const u16* __restrict__ A, const u16* __restrict__ Bt, int brow, int bcol, char* smem, const float* gnext) {
;     ...
;   const int ra = tid >> 2, cb = (tid & 3) * 8;
;   const u16* ga0 = A + (size_t)(brow + ra) * 1024 + cb;
;   const u16* ga1 = A + (size_t)(brow + 128 + ra) * 1024 + cb;
;   const u16* gb0 = Bt + (size_t)(bcol + ra) * 1024 + cb;
;   auto stage = [&](int t, int buf) {
;     char* sA = smem + buf * 24576; char* sB = sA + 16384;
;     if (MT >= 2 || tid < 256) __builtin_amdgcn_global_load_lds((const unsigned*)(ga0 + t * 32), (unsigned*)(sA + tid * 16), 16, 0, 0);
;     if (MT == 4) __builtin_amdgcn_global_load_lds((const unsigned*)(ga1 + t * 32), (unsigned*)(sA + 8192 + tid * 16), 16, 0, 0);
;     __builtin_amdgcn_global_load_lds((const unsigned*)(gb0 + t * 32), (unsigned*)(sB + tid * 16), 16, 0, 0);
;   };
;   stage(0, 0);
;   for (int t = 0; t < 32; ++t) {
;     asm volatile("s_waitcnt vmcnt(0)" ::: "memory");
;     __syncthreads();
;     if (t + 1 < 32) stage(t + 1, (t + 1) & 1);
;     const char* sA = smem + (t & 1) * 24576; const char* sB = sA + 16384;
;     bf16x8 Af[MT], Bf[4];
; #pragma unroll
;     for (int n = 0; n < 4; ++n) Bf[n] = *(const bf16x8*)(sB + (wc * 64 + n * 16 + fr) * 64 + fq * 16);
;     constexpr int MH = MT >= 2 ? MT / 2 : 1;
; #pragma unroll
;     for (int m = 0; m < MH; ++m) Af[m] = *(const bf16x8*)(sA + (wr * (16 * MT) + m * 16 + fr) * 64 + fq * 16);
;     __builtin_amdgcn_sched_barrier(0);
; #pragma unroll
;     for (int m = MH; m < MT; ++m) Af[m] = *(const bf16x8*)(sA + (wr * (16 * MT) + m * 16 + fr) * 64 + fq * 16);
; #pragma unroll
;     for (int m = 0; m < MH; ++m)
; #pragma unroll
;       for (int n = 0; n < 4; ++n)
;         acc[m][n] = SWAP ? __builtin_amdgcn_mfma_f32_16x16x32_bf16(Bf[n], Af[m], acc[m][n], 0, 0, 0)
;                          : __builtin_amdgcn_mfma_f32_16x16x32_bf16(Af[m], Bf[n], acc[m][n], 0, 0, 0);
;     __builtin_amdgcn_sched_barrier(0);
; #pragma unroll
;     for (int m = MH; m < MT; ++m)
; #pragma unroll
;       for (int n = 0; n < 4; ++n)
;         acc[m][n] = SWAP ? __builtin_amdgcn_mfma_f32_16x16x32_bf16(Bf[n], Af[m], acc[m][n], 0, 0, 0)
;                          : __builtin_amdgcn_mfma_f32_16x16x32_bf16(Af[m], Bf[n], acc[m][n], 0, 0, 0);
	v_ashrrev_i32_e32 v5, 31, v4
	v_lshlrev_b64 v[4:5], 11, v[4:5]
	v_or_b32_e32 v4, v4, v2
	v_bfe_u32 v75, v12, 4, 2
	v_or_b32_e32 v8, v8, v2
	v_lshl_add_u64 v[70:71], s[4:5], 0, v[4:5]
	v_mov_b32_e32 v4, 0
	s_mov_b32 s0, 0
	v_lshlrev_b32_e32 v77, 4, v75
	v_lshl_add_u64 v[68:69], s[20:21], 0, v[8:9]
	v_mov_b32_e32 v5, v4
	v_mov_b32_e32 v6, v4
	v_mov_b32_e32 v7, v4
	v_mov_b32_e32 v8, v4
	v_mov_b32_e32 v9, v4
	v_mov_b32_e32 v10, v4
	v_mov_b32_e32 v11, v4
	v_mov_b32_e32 v12, v4
	v_mov_b32_e32 v13, v4
	v_mov_b32_e32 v14, v4
	v_mov_b32_e32 v15, v4
	v_mov_b32_e32 v16, v4
	v_mov_b32_e32 v17, v4
	v_mov_b32_e32 v18, v4
	v_mov_b32_e32 v19, v4
	v_mov_b32_e32 v20, v4
	v_mov_b32_e32 v21, v4
	v_mov_b32_e32 v22, v4
	v_mov_b32_e32 v23, v4
	v_mov_b32_e32 v24, v4
	v_mov_b32_e32 v25, v4
	v_mov_b32_e32 v26, v4
	v_mov_b32_e32 v27, v4
	v_mov_b32_e32 v28, v4
	v_mov_b32_e32 v29, v4
	v_mov_b32_e32 v30, v4
	v_mov_b32_e32 v31, v4
	v_mov_b32_e32 v32, v4
	v_mov_b32_e32 v33, v4
	v_mov_b32_e32 v34, v4
	v_mov_b32_e32 v35, v4
	v_mov_b32_e32 v36, v4
	v_mov_b32_e32 v37, v4
	v_mov_b32_e32 v38, v4
	v_mov_b32_e32 v39, v4
	v_mov_b32_e32 v40, v4
	v_mov_b32_e32 v41, v4
	v_mov_b32_e32 v42, v4
	v_mov_b32_e32 v43, v4
	v_mov_b32_e32 v44, v4
	v_mov_b32_e32 v45, v4
	v_mov_b32_e32 v46, v4
	v_mov_b32_e32 v47, v4
	v_mov_b32_e32 v48, v4
	v_mov_b32_e32 v49, v4
	v_mov_b32_e32 v50, v4
	v_mov_b32_e32 v51, v4
	v_mov_b32_e32 v52, v4
	v_mov_b32_e32 v53, v4
	v_mov_b32_e32 v54, v4
	v_mov_b32_e32 v55, v4
	v_mov_b32_e32 v56, v4
	v_mov_b32_e32 v57, v4
	v_mov_b32_e32 v58, v4
	v_mov_b32_e32 v59, v4
	v_mov_b32_e32 v60, v4
	v_mov_b32_e32 v61, v4
	v_mov_b32_e32 v62, v4
	v_mov_b32_e32 v63, v4
	v_mov_b32_e32 v64, v4
	v_mov_b32_e32 v65, v4
	v_mov_b32_e32 v66, v4
	v_mov_b32_e32 v67, v4
	v_readlane_b32 s22, v127, 2
	v_readlane_b32 s23, v127, 3
	v_readfirstlane_b32 s98, v76
	s_movk_i32 s99, 0x6000
	s_add_i32 s101, s98, s99
	s_mov_b32 m0, s101
	s_add_i32 s101, s101, 0x2000
	global_load_lds_dwordx4 v[0:1], off
	s_mov_b32 m0, s101
	s_add_i32 s101, s101, 0x2000
	global_load_lds_dwordx4 v[68:69], off
	s_mov_b32 m0, s101
	s_add_i32 s99, s99, 0x6000
	global_load_lds_dwordx4 v[70:71], off
	s_cmp_eq_u32 s99, 0x12000
	s_cselect_b32 s99, 0, s99
	v_lshl_add_u64 v[0:1], v[0:1], 0, 64
	v_lshl_add_u64 v[68:69], v[68:69], 0, 64
	v_lshl_add_u64 v[70:71], v[70:71], 0, 64
	s_add_i32 s101, s98, s99
	s_mov_b32 m0, s101
	s_add_i32 s101, s101, 0x2000
	global_load_lds_dwordx4 v[0:1], off
	s_mov_b32 m0, s101
	s_add_i32 s101, s101, 0x2000
	global_load_lds_dwordx4 v[68:69], off
	s_mov_b32 m0, s101
	s_add_i32 s99, s99, 0x6000
	global_load_lds_dwordx4 v[70:71], off
	s_cmp_eq_u32 s99, 0x12000
	s_cselect_b32 s99, 0, s99
	v_lshl_add_u64 v[0:1], v[0:1], 0, 64
	v_lshl_add_u64 v[68:69], v[68:69], 0, 64
	v_lshl_add_u64 v[70:71], v[70:71], 0, 64
	s_mov_b32 s100, 0
	s_waitcnt vmcnt(6)
	s_barrier
	v_or_b32_e32 v112, s100, v77
	v_add_u32_e32 v113, v112, v78
	v_add_u32_e32 v112, v112, v79
	ds_read_b128 v[80:83], v113 offset:16384
	ds_read_b128 v[84:87], v113 offset:17408
	ds_read_b128 v[88:91], v113 offset:18432
	ds_read_b128 v[92:95], v113 offset:19456
	ds_read_b128 v[96:99], v112
	ds_read_b128 v[100:103], v112 offset:1024
	ds_read_b128 v[104:107], v112 offset:2048
	ds_read_b128 v[108:111], v112 offset:3072
	s_add_i32 s100, s100, 0x6000
	s_cmp_eq_u32 s100, 0x12000
	s_cselect_b32 s100, 0, s100
.LBB0_90:
	s_add_i32 s1, s0, 1
	s_waitcnt lgkmcnt(0)
	v_mfma_f32_16x16x32_bf16 v[64:67], v[96:99], v[80:83], v[64:67]
	v_mfma_f32_16x16x32_bf16 v[60:63], v[96:99], v[84:87], v[60:63]
	v_mfma_f32_16x16x32_bf16 v[56:59], v[96:99], v[88:91], v[56:59]
	v_mfma_f32_16x16x32_bf16 v[52:55], v[96:99], v[92:95], v[52:55]
	v_mfma_f32_16x16x32_bf16 v[48:51], v[100:103], v[80:83], v[48:51]
	v_mfma_f32_16x16x32_bf16 v[44:47], v[100:103], v[84:87], v[44:47]
	v_mfma_f32_16x16x32_bf16 v[40:43], v[100:103], v[88:91], v[40:43]
	v_mfma_f32_16x16x32_bf16 v[36:39], v[100:103], v[92:95], v[36:39]
	s_cmp_gt_u32 s0, 29
	s_cbranch_scc1 .Lpp_last_2
	s_waitcnt vmcnt(3)
	s_barrier
	s_cmp_gt_u32 s0, 28
	s_cbranch_scc1 .Lpp_nodma_2
	s_add_i32 s101, s98, s99
	s_mov_b32 m0, s101
	s_add_i32 s101, s101, 0x2000
	global_load_lds_dwordx4 v[0:1], off
	s_mov_b32 m0, s101
	s_add_i32 s101, s101, 0x2000
	global_load_lds_dwordx4 v[68:69], off
	s_mov_b32 m0, s101
	s_add_i32 s99, s99, 0x6000
	global_load_lds_dwordx4 v[70:71], off
	s_cmp_eq_u32 s99, 0x12000
	s_cselect_b32 s99, 0, s99
	v_lshl_add_u64 v[0:1], v[0:1], 0, 64
	v_lshl_add_u64 v[68:69], v[68:69], 0, 64
	v_lshl_add_u64 v[70:71], v[70:71], 0, 64
.Lpp_nodma_2:
	v_mfma_f32_16x16x32_bf16 v[32:35], v[104:107], v[80:83], v[32:35]
	v_mfma_f32_16x16x32_bf16 v[28:31], v[104:107], v[84:87], v[28:31]
	v_mfma_f32_16x16x32_bf16 v[24:27], v[104:107], v[88:91], v[24:27]
	v_mfma_f32_16x16x32_bf16 v[20:23], v[104:107], v[92:95], v[20:23]
	v_mfma_f32_16x16x32_bf16 v[16:19], v[108:111], v[80:83], v[16:19]
	v_mfma_f32_16x16x32_bf16 v[12:15], v[108:111], v[84:87], v[12:15]
	v_mfma_f32_16x16x32_bf16 v[8:11], v[108:111], v[88:91], v[8:11]
	v_mfma_f32_16x16x32_bf16 v[4:7], v[108:111], v[92:95], v[4:7]
	v_or_b32_e32 v112, s100, v77
	v_add_u32_e32 v113, v112, v78
	v_add_u32_e32 v112, v112, v79
	ds_read_b128 v[80:83], v113 offset:16384
	ds_read_b128 v[84:87], v113 offset:17408
	ds_read_b128 v[88:91], v113 offset:18432
	ds_read_b128 v[92:95], v113 offset:19456
	ds_read_b128 v[96:99], v112
	ds_read_b128 v[100:103], v112 offset:1024
	ds_read_b128 v[104:107], v112 offset:2048
	ds_read_b128 v[108:111], v112 offset:3072
	s_add_i32 s100, s100, 0x6000
	s_cmp_eq_u32 s100, 0x12000
	s_cselect_b32 s100, 0, s100
	s_mov_b32 s0, s1
	s_branch .LBB0_90
; template <int MODE, bool SWAP, int MT>
; DI void gemm_tile(const int wv_, const Params& p, const u16* __restrict__ A, const u16* __restrict__ Bt, int brow, int bcol, char* smem, const float* gnext) {
;     ...
;   for (int t = 0; t < 32; ++t) {
;     asm volatile("s_waitcnt vmcnt(0)" ::: "memory");
;     __syncthreads();
;     if (t + 1 < 32) stage(t + 1, (t + 1) & 1);
;     const char* sA = smem + (t & 1) * 24576; const char* sB = sA + 16384;
;     bf16x8 Af[MT], Bf[4];
; #pragma unroll
;     for (int n = 0; n < 4; ++n) Bf[n] = *(const bf16x8*)(sB + (wc * 64 + n * 16 + fr) * 64 + fq * 16);
;     constexpr int MH = MT >= 2 ? MT / 2 : 1;
; #pragma unroll
;     for (int m = 0; m < MH; ++m) Af[m] = *(const bf16x8*)(sA + (wr * (16 * MT) + m * 16 + fr) * 64 + fq * 16);
;     __builtin_amdgcn_sched_barrier(0);
; #pragma unroll
;     for (int m = MH; m < MT; ++m) Af[m] = *(const bf16x8*)(sA + (wr * (16 * MT) + m * 16 + fr) * 64 + fq * 16);
; #pragma unroll
;     for (int m = 0; m < MH; ++m)
; #pragma unroll
;       for (int n = 0; n < 4; ++n)
;         acc[m][n] = SWAP ? __builtin_amdgcn_mfma_f32_16x16x32_bf16(Bf[n], Af[m], acc[m][n], 0, 0, 0)
;                          : __builtin_amdgcn_mfma_f32_16x16x32_bf16(Af[m], Bf[n], acc[m][n], 0, 0, 0);
;     __builtin_amdgcn_sched_barrier(0);
; #pragma unroll
;     for (int m = MH; m < MT; ++m)
; #pragma unroll
;       for (int n = 0; n < 4; ++n)
;         acc[m][n] = SWAP ? __builtin_amdgcn_mfma_f32_16x16x32_bf16(Bf[n], Af[m], acc[m][n], 0, 0, 0)
;                          : __builtin_amdgcn_mfma_f32_16x16x32_bf16(Af[m], Bf[n], acc[m][n], 0, 0, 0);
;   }
;   __syncthreads();
;     ...
;       int R = brow + wr * (16 * MT) + m * 16 + fq * 4;
;       int b = R / P, pos = R - b * P;
;       const float rs0 = rowscale(p.ss, R), rs1 = rowscale(p.ss, R + 1), rs2 = rowscale(p.ss, R + 2), rs3 = rowscale(p.ss, R + 3);
.Lpp_last_2:
	v_mfma_f32_16x16x32_bf16 v[32:35], v[104:107], v[80:83], v[32:35]
	v_mfma_f32_16x16x32_bf16 v[28:31], v[104:107], v[84:87], v[28:31]
	v_mfma_f32_16x16x32_bf16 v[24:27], v[104:107], v[88:91], v[24:27]
	v_mfma_f32_16x16x32_bf16 v[20:23], v[104:107], v[92:95], v[20:23]
	v_mfma_f32_16x16x32_bf16 v[16:19], v[108:111], v[80:83], v[16:19]
	v_mfma_f32_16x16x32_bf16 v[12:15], v[108:111], v[84:87], v[12:15]
	v_mfma_f32_16x16x32_bf16 v[8:11], v[108:111], v[88:91], v[8:11]
	v_mfma_f32_16x16x32_bf16 v[4:7], v[108:111], v[92:95], v[4:7]
	s_mov_b32 s0, s1
	v_add_u32_e32 v0, v77, v79
	v_add_u32_e32 v1, v77, v78
	s_waitcnt vmcnt(0)
	s_waitcnt vmcnt(0)
	s_barrier
	ds_read_b128 v[68:71], v0 offset:25600
	ds_read_b128 v[80:83], v0 offset:24576
	ds_read_b128 v[76:79], v1 offset:44032
	ds_read_b128 v[84:87], v1 offset:43008
	ds_read_b128 v[88:91], v1 offset:41984
	ds_read_b128 v[92:95], v1 offset:40960
	s_waitcnt lgkmcnt(0)
	v_mfma_f32_16x16x32_bf16 v[64:67], v[80:83], v[92:95], v[64:67]
	v_mfma_f32_16x16x32_bf16 v[60:63], v[80:83], v[88:91], v[60:63]
	v_mfma_f32_16x16x32_bf16 v[56:59], v[80:83], v[84:87], v[56:59]
	v_mfma_f32_16x16x32_bf16 v[52:55], v[80:83], v[76:79], v[52:55]
	ds_read_b128 v[80:83], v0 offset:26624
	ds_read_b128 v[96:99], v0 offset:27648
	v_mfma_f32_16x16x32_bf16 v[48:51], v[68:71], v[92:95], v[48:51]
	v_mfma_f32_16x16x32_bf16 v[44:47], v[68:71], v[88:91], v[44:47]
	v_mfma_f32_16x16x32_bf16 v[40:43], v[68:71], v[84:87], v[40:43]
	v_mfma_f32_16x16x32_bf16 v[36:39], v[68:71], v[76:79], v[36:39]
	v_lshl_add_u32 v0, v74, 6, s18
	s_waitcnt lgkmcnt(0)
	v_mfma_f32_16x16x32_bf16 v[16:19], v[96:99], v[92:95], v[16:19]
	s_addk_i32 s15, 0xf600
	s_movk_i32 s19, 0xdf80
	v_mfma_f32_16x16x32_bf16 v[12:15], v[96:99], v[88:91], v[12:15]
	s_barrier
	s_mov_b32 s0, 0x358637bd
	v_mfma_f32_16x16x32_bf16 v[8:11], v[96:99], v[84:87], v[8:11]
	s_mov_b32 s18, 0x3a800000
	s_mov_b32 s20, 0x45800000
	v_mfma_f32_16x16x32_bf16 v[4:7], v[96:99], v[76:79], v[4:7]
	v_lshl_or_b32 v96, v75, 2, v0
	v_lshlrev_b32_e32 v0, 6, v72
	v_or3_b32 v2, v0, s15, v73
	s_mov_b32 s15, 0x7e07e07f
	v_mul_hi_i32 v0, v96, s15
	v_lshrrev_b32_e32 v1, 31, v0
	v_ashrrev_i32_e32 v0, 12, v0
	v_ashrrev_i32_e32 v97, 31, v96
	v_or_b32_e32 v68, 2, v96
	v_add_u32_e32 v70, v0, v1
	v_lshlrev_b64 v[0:1], 6, v[96:97]
	v_ashrrev_i32_e32 v69, 31, v68
	v_lshl_add_u64 v[0:1], s[90:91], 0, v[0:1]
	v_lshlrev_b64 v[68:69], 6, v[68:69]
	v_mfma_f32_16x16x32_bf16 v[32:35], v[80:83], v[92:95], v[32:35]
	v_mad_i32_i24 v98, v70, s19, v96
	v_lshl_add_u64 v[102:103], s[90:91], 0, v[68:69]
	v_lshl_or_b32 v97, v70, 9, v2
	v_mfma_f32_16x16x32_bf16 v[28:31], v[80:83], v[88:91], v[28:31]
	v_ashrrev_i32_e32 v99, 31, v98
	v_mfma_f32_16x16x32_bf16 v[24:27], v[80:83], v[84:87], v[24:27]
	v_mfma_f32_16x16x32_bf16 v[20:23], v[80:83], v[76:79], v[20:23]
	global_load_dwordx4 v[68:71], v[0:1], off offset:112
	global_load_dwordx4 v[72:75], v[0:1], off offset:48
	global_load_dwordx4 v[76:79], v[0:1], off offset:96
	global_load_dwordx4 v[80:83], v[0:1], off offset:32
	global_load_dwordx4 v[84:87], v[0:1], off offset:80
	global_load_dwordx4 v[88:91], v[0:1], off offset:16
	global_load_dwordx4 v[92:95], v[0:1], off offset:64
	global_load_dwordx4 v[104:107], v[0:1], off
	s_waitcnt vmcnt(1)
	v_mov_b32_e32 v1, v92
	s_waitcnt vmcnt(0)
	v_mov_b32_e32 v0, v104
	v_mov_b32_e32 v92, v105
	v_pk_add_f32 v[0:1], v[0:1], v[92:93]
	v_mov_b32_e32 v92, v106
	v_mov_b32_e32 v93, v94
	v_mov_b32_e32 v94, v107
	v_pk_add_f32 v[92:93], v[92:93], v[94:95]
	s_nop 0
	v_pk_add_f32 v[0:1], v[0:1], v[92:93]
	v_mov_b32_e32 v92, v88
	v_mov_b32_e32 v93, v84
	v_mov_b32_e32 v84, v89
	v_mov_b32_e32 v88, v90
	v_mov_b32_e32 v89, v86
	v_mov_b32_e32 v86, v91
	v_pk_add_f32 v[84:85], v[92:93], v[84:85]
	v_pk_add_f32 v[86:87], v[88:89], v[86:87]
	s_nop 0
	v_pk_add_f32 v[84:85], v[84:85], v[86:87]
	s_nop 0
	v_pk_add_f32 v[0:1], v[0:1], v[84:85]
	v_mov_b32_e32 v84, v80
	v_mov_b32_e32 v85, v76
	v_mov_b32_e32 v76, v81
	v_mov_b32_e32 v80, v82
	v_mov_b32_e32 v81, v78
	v_mov_b32_e32 v78, v83
	v_pk_add_f32 v[76:77], v[84:85], v[76:77]
	v_pk_add_f32 v[78:79], v[80:81], v[78:79]
	s_nop 0
	v_pk_add_f32 v[76:77], v[76:77], v[78:79]
	s_nop 0
	v_pk_add_f32 v[0:1], v[0:1], v[76:77]
	v_mov_b32_e32 v76, v72
	v_mov_b32_e32 v77, v68
	v_mov_b32_e32 v68, v73
	v_mov_b32_e32 v72, v74
	v_mov_b32_e32 v73, v70
	v_mov_b32_e32 v70, v75
	v_pk_add_f32 v[68:69], v[76:77], v[68:69]
	v_pk_add_f32 v[70:71], v[72:73], v[70:71]
	s_nop 0
	v_pk_add_f32 v[68:69], v[68:69], v[70:71]
	s_nop 0
	v_pk_add_f32 v[68:69], v[0:1], v[68:69]
	v_mov_b64_e32 v[0:1], s[0:1]
	v_pk_fma_f32 v[68:69], v[68:69], s[18:19], v[0:1] op_sel_hi:[1,0,0]
	s_nop 0
	v_mul_f32_e32 v70, 0x4b800000, v68
	v_cmp_gt_f32_e64 s[0:1], s96, v68
	v_cmp_gt_f32_e32 vcc, s96, v69
	s_nop 0
	v_cndmask_b32_e64 v68, v68, v70, s[0:1]
	v_mul_f32_e32 v70, 0x4b800000, v69
	v_cndmask_b32_e32 v69, v69, v70, vcc
	v_rsq_f32_e32 v68, v68
	v_rsq_f32_e32 v69, v69
	s_nop 0
	v_pk_mul_f32 v[70:71], v[68:69], s[20:21] op_sel_hi:[1,0]
	s_nop 0
	v_cndmask_b32_e32 v101, v69, v71, vcc
	v_cndmask_b32_e64 v100, v68, v70, s[0:1]
	global_load_dwordx4 v[68:71], v[102:103], off offset:112
	global_load_dwordx4 v[72:75], v[102:103], off offset:48
	global_load_dwordx4 v[76:79], v[102:103], off offset:96
	global_load_dwordx4 v[80:83], v[102:103], off offset:32
	global_load_dwordx4 v[84:87], v[102:103], off offset:80
	global_load_dwordx4 v[88:91], v[102:103], off offset:16
	global_load_dwordx4 v[92:95], v[102:103], off offset:64
	s_nop 0
	global_load_dwordx4 v[102:105], v[102:103], off
	v_pk_mul_f32 v[64:65], v[64:65], v[100:101]
	v_pk_mul_f32 v[52:53], v[52:53], v[100:101]
	v_cvt_pk_bf16_f32 v64, v64, v65
	v_cvt_pk_bf16_f32 v52, v52, v53
	v_pk_mul_f32 v[60:61], v[60:61], v[100:101]
	v_pk_mul_f32 v[56:57], v[56:57], v[100:101]
	v_cvt_pk_bf16_f32 v60, v60, v61
	v_cvt_pk_bf16_f32 v56, v56, v57
	s_waitcnt vmcnt(1)
; DI unsigned pack2(float a, float b) { f32x2_t v = {a, b}; return __builtin_bit_cast(unsigned, __builtin_convertvector(v, bf16x2_t)); }
; DI float rowscale(const float* ss, int R) {
;   const float4* q = (const float4*)(ss + (size_t)R * 16);
;   float4 a = q[0], b = q[1], c = q[2], d = q[3];
;   float t = ((a.x + a.y) + (a.z + a.w)) + ((b.x + b.y) + (b.z + b.w)) + ((c.x + c.y) + (c.z + c.w)) + ((d.x + d.y) + (d.z + d.w));
;   return rsqrtf(t * (1.f / 1024.f) + 1e-6f);
; }
; template <int MODE, bool SWAP, int MT>
; DI void gemm_tile(const int wv_, const Params& p, const u16* __restrict__ A, const u16* __restrict__ Bt, int brow, int bcol, char* smem, const float* gnext) {
;     ...
;       int R = brow + wr * (16 * MT) + m * 16 + fq * 4;
;       int b = R / P, pos = R - b * P;
;       const float rs0 = rowscale(p.ss, R), rs1 = rowscale(p.ss, R + 1), rs2 = rowscale(p.ss, R + 2), rs3 = rowscale(p.ss, R + 3);
; #pragma unroll
;       for (int n = 0; n < 4; ++n) {
;         int col = bcol + wc * 64 + n * 16 + fr - 2560;
;         uint2 o; o.x = pack2(acc[m][n][0] * rs0, acc[m][n][1] * rs1); o.y = pack2(acc[m][n][2] * rs2, acc[m][n][3] * rs3);
;         *(uint2*)(p.vt + ((size_t)(b * 512 + col)) * P + pos) = o;
	v_mov_b32_e32 v107, v92
	s_waitcnt vmcnt(0)
	v_mov_b32_e32 v106, v102
	v_mov_b32_e32 v92, v103
	v_mov_b32_e32 v102, v104
	v_mov_b32_e32 v103, v94
	v_mov_b32_e32 v94, v105
	v_pk_add_f32 v[92:93], v[106:107], v[92:93]
	v_pk_add_f32 v[94:95], v[102:103], v[94:95]
	s_nop 0
	v_pk_add_f32 v[92:93], v[92:93], v[94:95]
	v_mov_b32_e32 v94, v88
	v_mov_b32_e32 v95, v84
	v_mov_b32_e32 v84, v89
	v_mov_b32_e32 v88, v90
	v_mov_b32_e32 v89, v86
	v_mov_b32_e32 v86, v91
	v_pk_add_f32 v[84:85], v[94:95], v[84:85]
	v_pk_add_f32 v[86:87], v[88:89], v[86:87]
	s_nop 0
	v_pk_add_f32 v[84:85], v[84:85], v[86:87]
	v_mov_b32_e32 v86, v80
	v_mov_b32_e32 v87, v76
	v_mov_b32_e32 v76, v81
	v_mov_b32_e32 v80, v82
	v_mov_b32_e32 v81, v78
	v_mov_b32_e32 v78, v83
	v_pk_add_f32 v[76:77], v[86:87], v[76:77]
	v_pk_add_f32 v[78:79], v[80:81], v[78:79]
	v_pk_add_f32 v[84:85], v[92:93], v[84:85]
	v_pk_add_f32 v[76:77], v[76:77], v[78:79]
	v_mov_b32_e32 v78, v72
	v_mov_b32_e32 v79, v68
	v_mov_b32_e32 v68, v73
	v_mov_b32_e32 v72, v74
	v_mov_b32_e32 v73, v70
	v_mov_b32_e32 v70, v75
	v_pk_add_f32 v[68:69], v[78:79], v[68:69]
	v_pk_add_f32 v[70:71], v[72:73], v[70:71]
	v_pk_add_f32 v[76:77], v[84:85], v[76:77]
	v_pk_add_f32 v[68:69], v[68:69], v[70:71]
	v_mov_b64_e32 v[84:85], s[72:73]
	v_pk_add_f32 v[68:69], v[76:77], v[68:69]
	s_nop 0
	v_pk_fma_f32 v[68:69], v[68:69], s[18:19], v[0:1] op_sel_hi:[1,0,0]
	s_nop 0
	v_mul_f32_e32 v65, 0x4b800000, v68
	v_cmp_gt_f32_e64 s[0:1], s96, v68
	v_cmp_gt_f32_e32 vcc, s96, v69
	s_nop 0
	v_cndmask_b32_e64 v65, v68, v65, s[0:1]
	v_rsq_f32_e32 v68, v65
	v_mul_f32_e32 v65, 0x4b800000, v69
	v_cndmask_b32_e32 v65, v69, v65, vcc
	v_rsq_f32_e32 v69, v65
	s_nop 0
	v_pk_mul_f32 v[70:71], v[68:69], s[20:21] op_sel_hi:[1,0]
	s_nop 0
	v_cndmask_b32_e32 v69, v69, v71, vcc
	v_cndmask_b32_e64 v68, v68, v70, s[0:1]
	v_pk_mul_f32 v[54:55], v[54:55], v[68:69]
	s_movk_i32 s21, 0x4100
	v_cvt_pk_bf16_f32 v53, v54, v55
	v_or_b32_e32 v54, 48, v97
	v_lshlrev_b64 v[70:71], 1, v[98:99]
	v_mad_i64_i32 v[54:55], s[0:1], v54, s21, v[84:85]
	v_lshl_add_u64 v[54:55], v[54:55], 0, v[70:71]
	global_store_dwordx2 v[54:55], v[52:53], off
	v_or_b32_e32 v52, 16, v96
	v_mul_hi_i32 v53, v52, s15
	v_lshrrev_b32_e32 v54, 31, v53
	v_ashrrev_i32_e32 v53, 12, v53
	v_pk_mul_f32 v[62:63], v[62:63], v[68:69]
	v_pk_mul_f32 v[58:59], v[58:59], v[68:69]
	v_add_u32_e32 v54, v53, v54
	v_ashrrev_i32_e32 v53, 31, v52
	v_pk_mul_f32 v[66:67], v[66:67], v[68:69]
	v_cvt_pk_bf16_f32 v61, v62, v63
	v_or_b32_e32 v62, 16, v97
	v_cvt_pk_bf16_f32 v57, v58, v59
	v_or_b32_e32 v58, 32, v97
	v_mad_i32_i24 v86, v54, s19, v52
	v_lshlrev_b64 v[52:53], 6, v[52:53]
	v_cvt_pk_bf16_f32 v65, v66, v67
	v_mad_i64_i32 v[66:67], s[0:1], v97, s21, v[84:85]
	v_mad_i64_i32 v[62:63], s[0:1], v62, s21, v[84:85]
	v_mad_i64_i32 v[58:59], s[0:1], v58, s21, v[84:85]
	v_lshl_add_u64 v[82:83], s[90:91], 0, v[52:53]
	v_or_b32_e32 v52, 18, v96
	v_lshl_add_u64 v[66:67], v[66:67], 0, v[70:71]
	v_lshl_add_u64 v[62:63], v[62:63], 0, v[70:71]
	v_lshl_add_u64 v[58:59], v[58:59], 0, v[70:71]
	v_ashrrev_i32_e32 v53, 31, v52
	global_store_dwordx2 v[66:67], v[64:65], off
	global_store_dwordx2 v[62:63], v[60:61], off
	global_store_dwordx2 v[58:59], v[56:57], off
	v_lshlrev_b64 v[52:53], 6, v[52:53]
	v_lshl_add_u64 v[80:81], s[90:91], 0, v[52:53]
	v_lshl_or_b32 v90, v54, 9, v2
	global_load_dwordx4 v[52:55], v[82:83], off offset:112
	global_load_dwordx4 v[56:59], v[82:83], off offset:48
	global_load_dwordx4 v[60:63], v[82:83], off offset:96
	global_load_dwordx4 v[64:67], v[82:83], off offset:32
	global_load_dwordx4 v[68:71], v[82:83], off offset:80
	global_load_dwordx4 v[72:75], v[82:83], off offset:16
	global_load_dwordx4 v[76:79], v[82:83], off offset:64
	global_load_dwordx4 v[92:95], v[82:83], off
	v_ashrrev_i32_e32 v87, 31, v86
	s_waitcnt vmcnt(1)
	v_mov_b32_e32 v83, v76
	s_waitcnt vmcnt(0)
	v_mov_b32_e32 v82, v92
	v_mov_b32_e32 v76, v93
	v_pk_add_f32 v[76:77], v[82:83], v[76:77]
	v_mov_b32_e32 v82, v94
	v_mov_b32_e32 v83, v78
	v_mov_b32_e32 v78, v95
	v_pk_add_f32 v[78:79], v[82:83], v[78:79]
	s_nop 0
	v_pk_add_f32 v[76:77], v[76:77], v[78:79]
	v_mov_b32_e32 v78, v72
	v_mov_b32_e32 v79, v68
	v_mov_b32_e32 v68, v73
	v_mov_b32_e32 v72, v74
	v_mov_b32_e32 v73, v70
	v_mov_b32_e32 v70, v75
	v_pk_add_f32 v[68:69], v[78:79], v[68:69]
	v_pk_add_f32 v[70:71], v[72:73], v[70:71]
	s_nop 0
	v_pk_add_f32 v[68:69], v[68:69], v[70:71]
	v_mov_b32_e32 v70, v64
	v_mov_b32_e32 v71, v60
	v_mov_b32_e32 v60, v65
	v_mov_b32_e32 v64, v66
	v_mov_b32_e32 v65, v62
	v_mov_b32_e32 v62, v67
	v_pk_add_f32 v[60:61], v[70:71], v[60:61]
	v_pk_add_f32 v[62:63], v[64:65], v[62:63]
	v_pk_add_f32 v[68:69], v[76:77], v[68:69]
	v_pk_add_f32 v[60:61], v[60:61], v[62:63]
	v_mov_b32_e32 v62, v56
	v_mov_b32_e32 v63, v52
	v_mov_b32_e32 v52, v57
	v_mov_b32_e32 v56, v58
	v_mov_b32_e32 v57, v54
	v_mov_b32_e32 v54, v59
	v_pk_add_f32 v[52:53], v[62:63], v[52:53]
	v_pk_add_f32 v[54:55], v[56:57], v[54:55]
	v_pk_add_f32 v[60:61], v[68:69], v[60:61]
	v_pk_add_f32 v[52:53], v[52:53], v[54:55]
	s_nop 0
	v_pk_add_f32 v[52:53], v[60:61], v[52:53]
	s_nop 0
	v_pk_fma_f32 v[52:53], v[52:53], s[18:19], v[0:1] op_sel_hi:[1,0,0]
	s_nop 0
	v_mul_f32_e32 v54, 0x4b800000, v52
	v_cmp_gt_f32_e64 s[0:1], s96, v52
	v_cmp_gt_f32_e32 vcc, s96, v53
	s_nop 0
	v_cndmask_b32_e64 v52, v52, v54, s[0:1]
	v_mul_f32_e32 v54, 0x4b800000, v53
	v_cndmask_b32_e32 v53, v53, v54, vcc
	v_rsq_f32_e32 v52, v52
	v_rsq_f32_e32 v53, v53
	s_nop 0
	v_pk_mul_f32 v[54:55], v[52:53], s[20:21] op_sel_hi:[1,0]
	s_nop 0
	v_cndmask_b32_e32 v89, v53, v55, vcc
	v_cndmask_b32_e64 v88, v52, v54, s[0:1]
	global_load_dwordx4 v[52:55], v[80:81], off offset:112
	global_load_dwordx4 v[56:59], v[80:81], off offset:48
	global_load_dwordx4 v[60:63], v[80:81], off offset:96
	global_load_dwordx4 v[64:67], v[80:81], off offset:32
	global_load_dwordx4 v[68:71], v[80:81], off offset:80
	global_load_dwordx4 v[72:75], v[80:81], off offset:16
	global_load_dwordx4 v[76:79], v[80:81], off offset:64
	s_nop 0
	global_load_dwordx4 v[80:83], v[80:81], off
	v_pk_mul_f32 v[48:49], v[48:49], v[88:89]
	v_pk_mul_f32 v[36:37], v[36:37], v[88:89]
	v_cvt_pk_bf16_f32 v48, v48, v49
	v_cvt_pk_bf16_f32 v36, v36, v37
	v_pk_mul_f32 v[44:45], v[44:45], v[88:89]
	v_pk_mul_f32 v[40:41], v[40:41], v[88:89]
	v_cvt_pk_bf16_f32 v44, v44, v45
	v_cvt_pk_bf16_f32 v40, v40, v41
	s_waitcnt vmcnt(1)
; DI unsigned pack2(float a, float b) { f32x2_t v = {a, b}; return __builtin_bit_cast(unsigned, __builtin_convertvector(v, bf16x2_t)); }
; DI float rowscale(const float* ss, int R) {
;   const float4* q = (const float4*)(ss + (size_t)R * 16);
;   float4 a = q[0], b = q[1], c = q[2], d = q[3];
;   float t = ((a.x + a.y) + (a.z + a.w)) + ((b.x + b.y) + (b.z + b.w)) + ((c.x + c.y) + (c.z + c.w)) + ((d.x + d.y) + (d.z + d.w));
;   return rsqrtf(t * (1.f / 1024.f) + 1e-6f);
; }
; template <int MODE, bool SWAP, int MT>
; DI void gemm_tile(const int wv_, const Params& p, const u16* __restrict__ A, const u16* __restrict__ Bt, int brow, int bcol, char* smem, const float* gnext) {
;     ...
;       int R = brow + wr * (16 * MT) + m * 16 + fq * 4;
;       int b = R / P, pos = R - b * P;
;       const float rs0 = rowscale(p.ss, R), rs1 = rowscale(p.ss, R + 1), rs2 = rowscale(p.ss, R + 2), rs3 = rowscale(p.ss, R + 3);
; #pragma unroll
;       for (int n = 0; n < 4; ++n) {
;         int col = bcol + wc * 64 + n * 16 + fr - 2560;
;         uint2 o; o.x = pack2(acc[m][n][0] * rs0, acc[m][n][1] * rs1); o.y = pack2(acc[m][n][2] * rs2, acc[m][n][3] * rs3);
;         *(uint2*)(p.vt + ((size_t)(b * 512 + col)) * P + pos) = o;
	v_mov_b32_e32 v93, v76
	s_waitcnt vmcnt(0)
	v_mov_b32_e32 v92, v80
	v_mov_b32_e32 v76, v81
	v_mov_b32_e32 v80, v82
	v_mov_b32_e32 v81, v78
	v_mov_b32_e32 v78, v83
	v_pk_add_f32 v[76:77], v[92:93], v[76:77]
	v_pk_add_f32 v[78:79], v[80:81], v[78:79]
	s_nop 0
	v_pk_add_f32 v[76:77], v[76:77], v[78:79]
	v_mov_b32_e32 v78, v72
	v_mov_b32_e32 v79, v68
	v_mov_b32_e32 v68, v73
	v_mov_b32_e32 v72, v74
	v_mov_b32_e32 v73, v70
	v_mov_b32_e32 v70, v75
	v_pk_add_f32 v[68:69], v[78:79], v[68:69]
	v_pk_add_f32 v[70:71], v[72:73], v[70:71]
	s_nop 0
	v_pk_add_f32 v[68:69], v[68:69], v[70:71]
	v_mov_b32_e32 v70, v64
	v_mov_b32_e32 v71, v60
	v_mov_b32_e32 v60, v65
	v_mov_b32_e32 v64, v66
	v_mov_b32_e32 v65, v62
	v_mov_b32_e32 v62, v67
	v_pk_add_f32 v[60:61], v[70:71], v[60:61]
	v_pk_add_f32 v[62:63], v[64:65], v[62:63]
	v_pk_add_f32 v[68:69], v[76:77], v[68:69]
	v_pk_add_f32 v[60:61], v[60:61], v[62:63]
	v_mov_b32_e32 v62, v56
	v_mov_b32_e32 v63, v52
	v_mov_b32_e32 v52, v57
	v_mov_b32_e32 v56, v58
	v_mov_b32_e32 v57, v54
	v_mov_b32_e32 v54, v59
	v_pk_add_f32 v[52:53], v[62:63], v[52:53]
	v_pk_add_f32 v[54:55], v[56:57], v[54:55]
	v_pk_add_f32 v[60:61], v[68:69], v[60:61]
	v_pk_add_f32 v[52:53], v[52:53], v[54:55]
	s_nop 0
	v_pk_add_f32 v[52:53], v[60:61], v[52:53]
	s_nop 0
	v_pk_fma_f32 v[52:53], v[52:53], s[18:19], v[0:1] op_sel_hi:[1,0,0]
	s_nop 0
	v_mul_f32_e32 v49, 0x4b800000, v52
	v_cmp_gt_f32_e64 s[0:1], s96, v52
	v_cmp_gt_f32_e32 vcc, s96, v53
	s_nop 0
	v_cndmask_b32_e64 v49, v52, v49, s[0:1]
	v_rsq_f32_e32 v52, v49
	v_mul_f32_e32 v49, 0x4b800000, v53
	v_cndmask_b32_e32 v49, v53, v49, vcc
	v_rsq_f32_e32 v53, v49
	s_nop 0
	v_pk_mul_f32 v[54:55], v[52:53], s[20:21] op_sel_hi:[1,0]
	s_nop 0
	v_cndmask_b32_e32 v53, v53, v55, vcc
	v_cndmask_b32_e64 v52, v52, v54, s[0:1]
	v_pk_mul_f32 v[38:39], v[38:39], v[52:53]
	v_lshlrev_b64 v[54:55], 1, v[86:87]
	v_cvt_pk_bf16_f32 v37, v38, v39
	v_or_b32_e32 v38, 48, v90
	v_mad_i64_i32 v[38:39], s[0:1], v38, s21, v[84:85]
	v_lshl_add_u64 v[38:39], v[38:39], 0, v[54:55]
	global_store_dwordx2 v[38:39], v[36:37], off
	v_or_b32_e32 v36, 32, v96
	v_mul_hi_i32 v37, v36, s15
	v_lshrrev_b32_e32 v38, 31, v37
	v_ashrrev_i32_e32 v37, 12, v37
	v_pk_mul_f32 v[46:47], v[46:47], v[52:53]
	v_pk_mul_f32 v[42:43], v[42:43], v[52:53]
	v_add_u32_e32 v38, v37, v38
	v_ashrrev_i32_e32 v37, 31, v36
	v_pk_mul_f32 v[50:51], v[50:51], v[52:53]
	v_cvt_pk_bf16_f32 v45, v46, v47
	v_or_b32_e32 v46, 16, v90
	v_cvt_pk_bf16_f32 v41, v42, v43
	v_or_b32_e32 v42, 32, v90
	v_mad_i32_i24 v68, v38, s19, v36
	v_lshlrev_b64 v[36:37], 6, v[36:37]
	v_cvt_pk_bf16_f32 v49, v50, v51
	v_mad_i64_i32 v[50:51], s[0:1], v90, s21, v[84:85]
	v_mad_i64_i32 v[46:47], s[0:1], v46, s21, v[84:85]
	v_mad_i64_i32 v[42:43], s[0:1], v42, s21, v[84:85]
	v_lshl_add_u64 v[66:67], s[90:91], 0, v[36:37]
	v_or_b32_e32 v36, 34, v96
	v_lshl_add_u64 v[50:51], v[50:51], 0, v[54:55]
	v_lshl_add_u64 v[46:47], v[46:47], 0, v[54:55]
	v_lshl_add_u64 v[42:43], v[42:43], 0, v[54:55]
	v_ashrrev_i32_e32 v37, 31, v36
	global_store_dwordx2 v[50:51], v[48:49], off
	global_store_dwordx2 v[46:47], v[44:45], off
	global_store_dwordx2 v[42:43], v[40:41], off
	v_lshlrev_b64 v[36:37], 6, v[36:37]
	v_lshl_add_u64 v[64:65], s[90:91], 0, v[36:37]
	v_lshl_or_b32 v72, v38, 9, v2
	global_load_dwordx4 v[36:39], v[66:67], off offset:112
	global_load_dwordx4 v[40:43], v[66:67], off offset:48
	global_load_dwordx4 v[44:47], v[66:67], off offset:96
	global_load_dwordx4 v[48:51], v[66:67], off offset:32
	global_load_dwordx4 v[52:55], v[66:67], off offset:80
	global_load_dwordx4 v[56:59], v[66:67], off offset:16
	global_load_dwordx4 v[60:63], v[66:67], off offset:64
	global_load_dwordx4 v[74:77], v[66:67], off
	v_ashrrev_i32_e32 v69, 31, v68
	s_waitcnt vmcnt(1)
	v_mov_b32_e32 v67, v60
	s_waitcnt vmcnt(0)
	v_mov_b32_e32 v66, v74
	v_mov_b32_e32 v60, v75
	v_pk_add_f32 v[60:61], v[66:67], v[60:61]
	v_mov_b32_e32 v66, v76
	v_mov_b32_e32 v67, v62
	v_mov_b32_e32 v62, v77
	v_pk_add_f32 v[62:63], v[66:67], v[62:63]
	s_nop 0
	v_pk_add_f32 v[60:61], v[60:61], v[62:63]
	v_mov_b32_e32 v62, v56
	v_mov_b32_e32 v63, v52
	v_mov_b32_e32 v52, v57
	v_mov_b32_e32 v56, v58
	v_mov_b32_e32 v57, v54
	v_mov_b32_e32 v54, v59
	v_pk_add_f32 v[52:53], v[62:63], v[52:53]
	v_pk_add_f32 v[54:55], v[56:57], v[54:55]
	s_nop 0
	v_pk_add_f32 v[52:53], v[52:53], v[54:55]
	v_mov_b32_e32 v54, v48
	v_mov_b32_e32 v55, v44
	v_mov_b32_e32 v44, v49
	v_mov_b32_e32 v48, v50
	v_mov_b32_e32 v49, v46
	v_mov_b32_e32 v46, v51
	v_pk_add_f32 v[44:45], v[54:55], v[44:45]
	v_pk_add_f32 v[46:47], v[48:49], v[46:47]
	v_pk_add_f32 v[52:53], v[60:61], v[52:53]
	v_pk_add_f32 v[44:45], v[44:45], v[46:47]
	v_mov_b32_e32 v46, v40
	v_mov_b32_e32 v47, v36
	v_mov_b32_e32 v36, v41
	v_mov_b32_e32 v40, v42
	v_mov_b32_e32 v41, v38
	v_mov_b32_e32 v38, v43
	v_pk_add_f32 v[36:37], v[46:47], v[36:37]
	v_pk_add_f32 v[38:39], v[40:41], v[38:39]
	v_pk_add_f32 v[44:45], v[52:53], v[44:45]
	v_pk_add_f32 v[36:37], v[36:37], v[38:39]
	s_nop 0
	v_pk_add_f32 v[36:37], v[44:45], v[36:37]
	s_nop 0
	v_pk_fma_f32 v[36:37], v[36:37], s[18:19], v[0:1] op_sel_hi:[1,0,0]
	s_nop 0
	v_mul_f32_e32 v38, 0x4b800000, v36
	v_cmp_gt_f32_e64 s[0:1], s96, v36
	v_cmp_gt_f32_e32 vcc, s96, v37
	s_nop 0
	v_cndmask_b32_e64 v36, v36, v38, s[0:1]
	v_mul_f32_e32 v38, 0x4b800000, v37
	v_cndmask_b32_e32 v37, v37, v38, vcc
	v_rsq_f32_e32 v36, v36
	v_rsq_f32_e32 v37, v37
	s_nop 0
	v_pk_mul_f32 v[38:39], v[36:37], s[20:21] op_sel_hi:[1,0]
	s_nop 0
	v_cndmask_b32_e32 v71, v37, v39, vcc
	v_cndmask_b32_e64 v70, v36, v38, s[0:1]
	global_load_dwordx4 v[36:39], v[64:65], off offset:112
	global_load_dwordx4 v[40:43], v[64:65], off offset:48
	global_load_dwordx4 v[44:47], v[64:65], off offset:96
	global_load_dwordx4 v[48:51], v[64:65], off offset:32
	global_load_dwordx4 v[52:55], v[64:65], off offset:80
	global_load_dwordx4 v[56:59], v[64:65], off offset:16
	global_load_dwordx4 v[60:63], v[64:65], off offset:64
	s_nop 0
	global_load_dwordx4 v[64:67], v[64:65], off
	v_pk_mul_f32 v[32:33], v[32:33], v[70:71]
	v_pk_mul_f32 v[20:21], v[20:21], v[70:71]
	v_cvt_pk_bf16_f32 v32, v32, v33
	v_cvt_pk_bf16_f32 v20, v20, v21
	v_pk_mul_f32 v[28:29], v[28:29], v[70:71]
	v_pk_mul_f32 v[24:25], v[24:25], v[70:71]
	v_cvt_pk_bf16_f32 v28, v28, v29
	v_cvt_pk_bf16_f32 v24, v24, v25
	s_waitcnt vmcnt(1)
; DI unsigned pack2(float a, float b) { f32x2_t v = {a, b}; return __builtin_bit_cast(unsigned, __builtin_convertvector(v, bf16x2_t)); }
; DI float rowscale(const float* ss, int R) {
;   const float4* q = (const float4*)(ss + (size_t)R * 16);
;   float4 a = q[0], b = q[1], c = q[2], d = q[3];
;   float t = ((a.x + a.y) + (a.z + a.w)) + ((b.x + b.y) + (b.z + b.w)) + ((c.x + c.y) + (c.z + c.w)) + ((d.x + d.y) + (d.z + d.w));
;   return rsqrtf(t * (1.f / 1024.f) + 1e-6f);
; }
; template <int MODE, bool SWAP, int MT>
; DI void gemm_tile(const int wv_, const Params& p, const u16* __restrict__ A, const u16* __restrict__ Bt, int brow, int bcol, char* smem, const float* gnext) {
;     ...
;       int R = brow + wr * (16 * MT) + m * 16 + fq * 4;
;       int b = R / P, pos = R - b * P;
;       const float rs0 = rowscale(p.ss, R), rs1 = rowscale(p.ss, R + 1), rs2 = rowscale(p.ss, R + 2), rs3 = rowscale(p.ss, R + 3);
; #pragma unroll
;       for (int n = 0; n < 4; ++n) {
;         int col = bcol + wc * 64 + n * 16 + fr - 2560;
;         uint2 o; o.x = pack2(acc[m][n][0] * rs0, acc[m][n][1] * rs1); o.y = pack2(acc[m][n][2] * rs2, acc[m][n][3] * rs3);
;         *(uint2*)(p.vt + ((size_t)(b * 512 + col)) * P + pos) = o;
	v_mov_b32_e32 v75, v60
	s_waitcnt vmcnt(0)
	v_mov_b32_e32 v74, v64
	v_mov_b32_e32 v60, v65
	v_mov_b32_e32 v64, v66
	v_mov_b32_e32 v65, v62
	v_mov_b32_e32 v62, v67
	v_pk_add_f32 v[60:61], v[74:75], v[60:61]
	v_pk_add_f32 v[62:63], v[64:65], v[62:63]
	s_nop 0
	v_pk_add_f32 v[60:61], v[60:61], v[62:63]
	v_mov_b32_e32 v62, v56
	v_mov_b32_e32 v63, v52
	v_mov_b32_e32 v52, v57
	v_mov_b32_e32 v56, v58
	v_mov_b32_e32 v57, v54
	v_mov_b32_e32 v54, v59
	v_pk_add_f32 v[52:53], v[62:63], v[52:53]
	v_pk_add_f32 v[54:55], v[56:57], v[54:55]
	s_nop 0
	v_pk_add_f32 v[52:53], v[52:53], v[54:55]
	v_mov_b32_e32 v54, v48
	v_mov_b32_e32 v55, v44
	v_mov_b32_e32 v44, v49
	v_mov_b32_e32 v48, v50
	v_mov_b32_e32 v49, v46
	v_mov_b32_e32 v46, v51
	v_pk_add_f32 v[44:45], v[54:55], v[44:45]
	v_pk_add_f32 v[46:47], v[48:49], v[46:47]
	v_pk_add_f32 v[52:53], v[60:61], v[52:53]
	v_pk_add_f32 v[44:45], v[44:45], v[46:47]
	v_mov_b32_e32 v46, v40
	v_mov_b32_e32 v47, v36
	v_mov_b32_e32 v36, v41
	v_mov_b32_e32 v40, v42
	v_mov_b32_e32 v41, v38
	v_mov_b32_e32 v38, v43
	v_pk_add_f32 v[36:37], v[46:47], v[36:37]
	v_pk_add_f32 v[38:39], v[40:41], v[38:39]
	v_pk_add_f32 v[44:45], v[52:53], v[44:45]
	v_pk_add_f32 v[36:37], v[36:37], v[38:39]
	s_nop 0
	v_pk_add_f32 v[36:37], v[44:45], v[36:37]
	s_nop 0
	v_pk_fma_f32 v[36:37], v[36:37], s[18:19], v[0:1] op_sel_hi:[1,0,0]
	s_nop 0
	v_mul_f32_e32 v33, 0x4b800000, v36
	v_cmp_gt_f32_e64 s[0:1], s96, v36
	v_cmp_gt_f32_e32 vcc, s96, v37
	s_nop 0
	v_cndmask_b32_e64 v33, v36, v33, s[0:1]
	v_rsq_f32_e32 v36, v33
	v_mul_f32_e32 v33, 0x4b800000, v37
	v_cndmask_b32_e32 v33, v37, v33, vcc
	v_rsq_f32_e32 v37, v33
	s_nop 0
	v_pk_mul_f32 v[38:39], v[36:37], s[20:21] op_sel_hi:[1,0]
	s_nop 0
	v_cndmask_b32_e32 v37, v37, v39, vcc
	v_cndmask_b32_e64 v36, v36, v38, s[0:1]
	v_pk_mul_f32 v[22:23], v[22:23], v[36:37]
	v_lshlrev_b64 v[38:39], 1, v[68:69]
	v_cvt_pk_bf16_f32 v21, v22, v23
	v_or_b32_e32 v22, 48, v72
	v_mad_i64_i32 v[22:23], s[0:1], v22, s21, v[84:85]
	v_lshl_add_u64 v[22:23], v[22:23], 0, v[38:39]
	global_store_dwordx2 v[22:23], v[20:21], off
	v_or_b32_e32 v20, 48, v96
	v_mul_hi_i32 v21, v20, s15
	v_lshrrev_b32_e32 v22, 31, v21
	v_ashrrev_i32_e32 v21, 12, v21
	v_add_u32_e32 v40, v21, v22
	v_ashrrev_i32_e32 v21, 31, v20
	v_pk_mul_f32 v[30:31], v[30:31], v[36:37]
	v_pk_mul_f32 v[26:27], v[26:27], v[36:37]
	v_mad_i32_i24 v52, v40, s19, v20
	v_lshlrev_b64 v[20:21], 6, v[20:21]
	v_pk_mul_f32 v[34:35], v[34:35], v[36:37]
	v_cvt_pk_bf16_f32 v29, v30, v31
	v_or_b32_e32 v30, 16, v72
	v_cvt_pk_bf16_f32 v25, v26, v27
	v_or_b32_e32 v26, 32, v72
	v_lshl_add_u64 v[48:49], s[90:91], 0, v[20:21]
	v_or_b32_e32 v20, 50, v96
	v_cvt_pk_bf16_f32 v33, v34, v35
	v_mad_i64_i32 v[34:35], s[0:1], v72, s21, v[84:85]
	v_mad_i64_i32 v[30:31], s[0:1], v30, s21, v[84:85]
	v_mad_i64_i32 v[26:27], s[0:1], v26, s21, v[84:85]
	v_ashrrev_i32_e32 v21, 31, v20
	v_lshl_add_u64 v[34:35], v[34:35], 0, v[38:39]
	v_lshl_add_u64 v[30:31], v[30:31], 0, v[38:39]
	v_lshl_add_u64 v[26:27], v[26:27], 0, v[38:39]
	v_lshlrev_b64 v[20:21], 6, v[20:21]
	global_store_dwordx2 v[34:35], v[32:33], off
	global_store_dwordx2 v[30:31], v[28:29], off
	global_store_dwordx2 v[26:27], v[24:25], off
	v_lshl_add_u64 v[32:33], s[90:91], 0, v[20:21]
	global_load_dwordx4 v[20:23], v[32:33], off offset:48
	global_load_dwordx4 v[24:27], v[32:33], off offset:16
	global_load_dwordx4 v[28:31], v[32:33], off
	s_nop 0
	global_load_dwordx4 v[32:35], v[32:33], off offset:32
	v_lshl_or_b32 v2, v40, 9, v2
	v_ashrrev_i32_e32 v53, 31, v52
	s_waitcnt vmcnt(3)
	v_mov_b32_e32 v37, v22
	v_mov_b32_e32 v36, v21
	s_waitcnt vmcnt(1)
	v_mov_b32_e32 v22, v29
	v_pk_add_f32 v[28:29], v[28:29], v[22:23]
	v_mov_b32_e32 v22, v31
	v_pk_add_f32 v[30:31], v[30:31], v[22:23]
	v_mov_b32_e32 v22, v25
	v_mov_b32_e32 v21, v23
	v_pk_add_f32 v[24:25], v[24:25], v[22:23]
	v_mov_b32_e32 v22, v27
	v_pk_add_f32 v[20:21], v[36:37], v[20:21]
	v_pk_add_f32 v[26:27], v[26:27], v[22:23]
	v_pk_add_f32 v[56:57], v[20:21], v[20:21] op_sel:[0,1] op_sel_hi:[1,0]
	v_or_b32_e32 v20, 51, v96
	s_waitcnt vmcnt(0)
	v_mov_b32_e32 v29, v32
	v_mov_b32_e32 v31, v33
	v_mov_b32_e32 v25, v34
	v_mov_b32_e32 v27, v35
	v_ashrrev_i32_e32 v21, 31, v20
	v_pk_add_f32 v[28:29], v[28:29], v[30:31]
	v_pk_add_f32 v[24:25], v[24:25], v[26:27]
	v_lshlrev_b64 v[20:21], 6, v[20:21]
	v_pk_add_f32 v[24:25], v[28:29], v[24:25]
	v_lshl_add_u64 v[32:33], s[90:91], 0, v[20:21]
	v_pk_add_f32 v[54:55], v[24:25], v[24:25] op_sel:[0,1] op_sel_hi:[1,0]
	global_load_dwordx4 v[20:23], v[32:33], off offset:32
	global_load_dwordx4 v[24:27], v[32:33], off offset:16
	global_load_dwordx4 v[28:31], v[32:33], off
	s_nop 0
	global_load_dwordx4 v[32:35], v[32:33], off offset:48
	s_waitcnt vmcnt(2)
	v_mov_b32_e32 v38, v25
	s_waitcnt vmcnt(1)
; DI unsigned pack2(float a, float b) { f32x2_t v = {a, b}; return __builtin_bit_cast(unsigned, __builtin_convertvector(v, bf16x2_t)); }
; template <int MODE, bool SWAP, int MT>
; DI void gemm_tile(const int wv_, const Params& p, const u16* __restrict__ A, const u16* __restrict__ Bt, int brow, int bcol, char* smem, const float* gnext) {
;     ...
;       int R = brow + wr * (16 * MT) + m * 16 + fq * 4;
;       int b = R / P, pos = R - b * P;
;       const float rs0 = rowscale(p.ss, R), rs1 = rowscale(p.ss, R + 1), rs2 = rowscale(p.ss, R + 2), rs3 = rowscale(p.ss, R + 3);
; #pragma unroll
;       for (int n = 0; n < 4; ++n) {
;         int col = bcol + wc * 64 + n * 16 + fr - 2560;
;         uint2 o; o.x = pack2(acc[m][n][0] * rs0, acc[m][n][1] * rs1); o.y = pack2(acc[m][n][2] * rs2, acc[m][n][3] * rs3);
;         *(uint2*)(p.vt + ((size_t)(b * 512 + col)) * P + pos) = o;
	v_mov_b32_e32 v36, v29
	v_mov_b32_e32 v37, v30
	v_mov_b32_e32 v39, v26
	v_mov_b32_e32 v29, v31
	v_mov_b32_e32 v25, v27
	v_mov_b32_e32 v26, v21
	v_pk_add_f32 v[28:29], v[36:37], v[28:29]
	v_pk_add_f32 v[24:25], v[38:39], v[24:25]
	v_pk_add_f32 v[20:21], v[20:21], v[26:27]
	v_mov_b32_e32 v26, v23
	v_pk_add_f32 v[28:29], v[28:29], v[28:29] op_sel:[0,1] op_sel_hi:[1,0]
	v_pk_add_f32 v[24:25], v[24:25], v[24:25] op_sel:[0,1] op_sel_hi:[1,0]
	v_pk_add_f32 v[22:23], v[22:23], v[26:27]
	s_waitcnt vmcnt(0)
	v_mov_b32_e32 v29, v32
	v_mov_b32_e32 v25, v33
	v_mov_b32_e32 v21, v34
	v_mov_b32_e32 v23, v35
	v_pk_add_f32 v[24:25], v[28:29], v[24:25]
	v_pk_add_f32 v[20:21], v[20:21], v[22:23]
	s_nop 0
	v_pk_add_f32 v[58:59], v[24:25], v[20:21]
	global_load_dwordx4 v[20:23], v[48:49], off offset:112
	global_load_dwordx4 v[24:27], v[48:49], off offset:48
	global_load_dwordx4 v[28:31], v[48:49], off offset:96
	global_load_dwordx4 v[32:35], v[48:49], off offset:32
	global_load_dwordx4 v[36:39], v[48:49], off offset:80
	global_load_dwordx4 v[40:43], v[48:49], off offset:16
	global_load_dwordx4 v[44:47], v[48:49], off offset:64
	s_nop 0
	global_load_dwordx4 v[48:51], v[48:49], off
	v_mov_b32_e32 v55, v58
	v_mov_b32_e32 v57, v59
	s_waitcnt vmcnt(1)
	v_mov_b32_e32 v61, v44
	s_waitcnt vmcnt(0)
	v_mov_b32_e32 v60, v48
	v_mov_b32_e32 v44, v49
	v_mov_b32_e32 v48, v50
	v_mov_b32_e32 v49, v46
	v_mov_b32_e32 v46, v51
	v_pk_add_f32 v[44:45], v[60:61], v[44:45]
	v_pk_add_f32 v[46:47], v[48:49], v[46:47]
	s_nop 0
	v_pk_add_f32 v[44:45], v[44:45], v[46:47]
	v_mov_b32_e32 v46, v40
	v_mov_b32_e32 v47, v36
	v_mov_b32_e32 v36, v41
	v_mov_b32_e32 v40, v42
	v_mov_b32_e32 v41, v38
	v_mov_b32_e32 v38, v43
	v_pk_add_f32 v[36:37], v[46:47], v[36:37]
	v_pk_add_f32 v[38:39], v[40:41], v[38:39]
	s_nop 0
	v_pk_add_f32 v[36:37], v[36:37], v[38:39]
	v_mov_b32_e32 v38, v32
	v_mov_b32_e32 v39, v28
	v_mov_b32_e32 v28, v33
	v_mov_b32_e32 v32, v34
	v_mov_b32_e32 v33, v30
	v_mov_b32_e32 v30, v35
	v_pk_add_f32 v[28:29], v[38:39], v[28:29]
	v_pk_add_f32 v[30:31], v[32:33], v[30:31]
	v_pk_add_f32 v[36:37], v[44:45], v[36:37]
	v_pk_add_f32 v[28:29], v[28:29], v[30:31]
	v_mov_b32_e32 v30, v24
	v_mov_b32_e32 v31, v20
	v_mov_b32_e32 v20, v25
	v_mov_b32_e32 v24, v26
	v_mov_b32_e32 v25, v22
	v_mov_b32_e32 v22, v27
	v_pk_add_f32 v[20:21], v[30:31], v[20:21]
	v_pk_add_f32 v[22:23], v[24:25], v[22:23]
	v_pk_add_f32 v[28:29], v[36:37], v[28:29]
	v_pk_add_f32 v[20:21], v[20:21], v[22:23]
	s_nop 0
	v_pk_add_f32 v[20:21], v[28:29], v[20:21]
	s_nop 0
	v_pk_fma_f32 v[20:21], v[20:21], s[18:19], v[0:1] op_sel_hi:[1,0,0]
	s_nop 0
	v_mul_f32_e32 v22, 0x4b800000, v20
	v_cmp_gt_f32_e64 s[0:1], s96, v20
	v_cmp_gt_f32_e32 vcc, s96, v21
	s_nop 0
	v_cndmask_b32_e64 v20, v20, v22, s[0:1]
	v_mul_f32_e32 v22, 0x4b800000, v21
	v_cndmask_b32_e32 v21, v21, v22, vcc
	v_rsq_f32_e32 v20, v20
	v_rsq_f32_e32 v21, v21
	s_nop 0
	v_pk_mul_f32 v[22:23], v[20:21], s[20:21] op_sel_hi:[1,0]
	s_nop 0
	v_cndmask_b32_e32 v21, v21, v23, vcc
	v_cndmask_b32_e64 v20, v20, v22, s[0:1]
	v_pk_add_f32 v[22:23], v[54:55], v[56:57]
	v_pk_mul_f32 v[16:17], v[16:17], v[20:21]
	v_pk_fma_f32 v[0:1], v[22:23], s[18:19], v[0:1] op_sel_hi:[1,0,0]
	v_cvt_pk_bf16_f32 v16, v16, v17
	v_mul_f32_e32 v17, 0x4b800000, v0
	v_cmp_gt_f32_e64 s[0:1], s96, v0
	v_cmp_gt_f32_e32 vcc, s96, v1
	v_pk_mul_f32 v[8:9], v[8:9], v[20:21]
	v_cndmask_b32_e64 v0, v0, v17, s[0:1]
	v_mul_f32_e32 v17, 0x4b800000, v1
	v_cndmask_b32_e32 v1, v1, v17, vcc
	v_rsq_f32_e32 v0, v0
	v_rsq_f32_e32 v1, v1
	v_cvt_pk_bf16_f32 v8, v8, v9
	v_pk_mul_f32 v[12:13], v[12:13], v[20:21]
	v_pk_mul_f32 v[4:5], v[4:5], v[20:21]
	v_pk_mul_f32 v[22:23], v[0:1], s[20:21] op_sel_hi:[1,0]
	v_cvt_pk_bf16_f32 v12, v12, v13
	v_cndmask_b32_e32 v1, v1, v23, vcc
	v_cndmask_b32_e64 v0, v0, v22, s[0:1]
	v_pk_mul_f32 v[10:11], v[10:11], v[0:1]
	v_lshlrev_b64 v[22:23], 1, v[52:53]
	v_cvt_pk_bf16_f32 v9, v10, v11
	v_or_b32_e32 v10, 32, v2
	v_mad_i64_i32 v[10:11], s[0:1], v10, s21, v[84:85]
	v_pk_mul_f32 v[14:15], v[14:15], v[0:1]
	v_lshl_add_u64 v[10:11], v[10:11], 0, v[22:23]
	v_pk_mul_f32 v[18:19], v[18:19], v[0:1]
	v_cvt_pk_bf16_f32 v13, v14, v15
	v_or_b32_e32 v14, 16, v2
	global_store_dwordx2 v[10:11], v[8:9], off
	v_cvt_pk_bf16_f32 v8, v4, v5
	v_pk_mul_f32 v[4:5], v[6:7], v[0:1]
	v_or_b32_e32 v0, 48, v2
	v_cvt_pk_bf16_f32 v17, v18, v19
	v_mad_i64_i32 v[18:19], s[0:1], v2, s21, v[84:85]
	v_mad_i64_i32 v[14:15], s[0:1], v14, s21, v[84:85]
	v_mad_i64_i32 v[0:1], s[0:1], v0, s21, v[84:85]
	v_lshl_add_u64 v[18:19], v[18:19], 0, v[22:23]
	v_lshl_add_u64 v[14:15], v[14:15], 0, v[22:23]
	v_lshl_add_u64 v[6:7], v[0:1], 0, v[22:23]
	global_store_dwordx2 v[18:19], v[16:17], off
	global_store_dwordx2 v[14:15], v[12:13], off
	global_store_dword v[6:7], v8, off
	s_branch .LBB0_83

; template <int MODE, bool SWAP, int MT>
; DI void gemm_tile(const int wv_, const Params& p, const u16* __restrict__ A, const u16* __restrict__ Bt, int brow, int bcol, char* smem, const float* gnext) {
;     ...
;   const int tid = tid_, wid = tid >> 6, lane = tid & 63, wr = wid >> 1, wc = wid & 1, fr = lane & 15, fq = lane >> 4;
;   f32x4 acc[MT][4];
; #pragma unroll
;   for (int m = 0; m < MT; ++m)
; #pragma unroll
;     for (int n = 0; n < 4; ++n) acc[m][n] = f32x4{0.f, 0.f, 0.f, 0.f};
;   const int ra = tid >> 2, cb = (tid & 3) * 8;
;   const u16* ga0 = A + (size_t)(brow + ra) * 1024 + cb;
;   const u16* ga1 = A + (size_t)(brow + 128 + ra) * 1024 + cb;
;   const u16* gb0 = Bt + (size_t)(bcol + ra) * 1024 + cb;
;   auto stage = [&](int t, int buf) {
;     char* sA = smem + buf * 24576; char* sB = sA + 16384;
;     if (MT >= 2 || tid < 256) __builtin_amdgcn_global_load_lds((const unsigned*)(ga0 + t * 32), (unsigned*)(sA + tid * 16), 16, 0, 0);
;     if (MT == 4) __builtin_amdgcn_global_load_lds((const unsigned*)(ga1 + t * 32), (unsigned*)(sA + 8192 + tid * 16), 16, 0, 0);
;     __builtin_amdgcn_global_load_lds((const unsigned*)(gb0 + t * 32), (unsigned*)(sB + tid * 16), 16, 0, 0);
;   };
;   stage(0, 0);
.LBB0_372:
	s_mul_hi_i32 s0, s22, 0x3e0f83e1
	s_mov_b32 s7, 0
	s_lshr_b32 s1, s0, 31
	s_ashr_i32 s0, s0, 3
	s_add_i32 s6, s0, s1
	v_mbcnt_lo_u32_b32 v0, -1, s7
	v_mbcnt_hi_u32_b32 v0, -1, v0
	s_mul_i32 s0, s6, 0xffffffdf
	v_add_u32_e32 v2, s33, v0
	s_add_i32 s1, s0, s22
	s_lshl_b32 s0, s6, 8
	s_mov_b32 s7, s16
	v_ashrrev_i32_e32 v12, 2, v2
	v_add_u32_e32 v0, s0, v12
	s_mov_b32 s7, s17
	v_ashrrev_i32_e32 v1, 31, v0
	v_readlane_b32 s8, v127, 0
	v_lshlrev_b64 v[4:5], 11, v[0:1]
	v_readlane_b32 s9, v127, 1
	v_lshlrev_b32_e32 v76, 4, v2
	v_bfe_u32 v72, v2, 6, 1
	v_ashrrev_i32_e32 v74, 7, v2
	v_and_b32_e32 v75, 15, v2
	v_bfe_u32 v73, v2, 4, 2
	v_lshl_add_u64 v[6:7], s[8:9], 0, v[4:5]
	v_and_b32_e32 v2, 48, v76
	v_add_u32_e32 v0, 0x80, v0
	v_readfirstlane_b32 s7, v76
	v_lshl_add_u64 v[6:7], v[6:7], 0, v[2:3]
	v_ashrrev_i32_e32 v1, 31, v0
	s_mov_b32 m0, s7
	s_lshl_b32 s23, s1, 7
	v_lshlrev_b64 v[8:9], 11, v[0:1]
	global_load_lds_dwordx4 v[6:7], off
	v_add_u32_e32 v6, 0x2000, v76
	v_lshl_add_u64 v[0:1], s[8:9], 0, v[8:9]
	v_add_u32_e32 v10, s23, v12
	v_readfirstlane_b32 s7, v6
	v_lshl_add_u64 v[0:1], v[0:1], 0, v[2:3]
	v_ashrrev_i32_e32 v11, 31, v10
	s_mov_b32 m0, s7
	v_lshlrev_b64 v[10:11], 11, v[10:11]
	global_load_lds_dwordx4 v[0:1], off
	v_add_u32_e32 v0, 0x4000, v76
	v_lshl_add_u64 v[10:11], s[2:3], 0, v[10:11]
	v_readfirstlane_b32 s7, v0
	v_lshl_add_u64 v[10:11], v[10:11], 0, v[2:3]
	s_mov_b32 m0, s7
	v_readlane_b32 s8, v127, 22
	global_load_lds_dwordx4 v[10:11], off
	v_lshlrev_b32_e32 v0, 6, v75
	v_or_b32_e32 v4, v4, v2
	v_readlane_b32 s9, v127, 23
	v_lshl_or_b32 v78, v72, 12, v0
	v_lshl_or_b32 v79, v74, 12, v0
	v_lshl_add_u64 v[0:1], s[8:9], 0, v[4:5]
	v_add_u32_e32 v4, s20, v12
	s_mulk_i32 s6, 0x1080
	v_subrev_u32_e32 v4, s6, v4
	v_ashrrev_i32_e32 v5, 31, v4
	v_lshlrev_b64 v[4:5], 11, v[4:5]
	v_or_b32_e32 v4, v4, v2
	v_or_b32_e32 v8, v8, v2
	v_lshl_add_u64 v[70:71], s[4:5], 0, v[4:5]
	v_mov_b32_e32 v4, 0
	s_mov_b32 s1, 0
	v_lshlrev_b32_e32 v77, 4, v73
	v_lshl_add_u64 v[68:69], s[8:9], 0, v[8:9]
	v_mov_b32_e32 v5, v4
	v_mov_b32_e32 v6, v4
	v_mov_b32_e32 v7, v4
	v_mov_b32_e32 v8, v4
	v_mov_b32_e32 v9, v4
	v_mov_b32_e32 v10, v4
	v_mov_b32_e32 v11, v4
	v_mov_b32_e32 v12, v4
	v_mov_b32_e32 v13, v4
	v_mov_b32_e32 v14, v4
	v_mov_b32_e32 v15, v4
	v_mov_b32_e32 v16, v4
	v_mov_b32_e32 v17, v4
	v_mov_b32_e32 v18, v4
	v_mov_b32_e32 v19, v4
	v_mov_b32_e32 v20, v4
	v_mov_b32_e32 v21, v4
	v_mov_b32_e32 v22, v4
	v_mov_b32_e32 v23, v4
	v_mov_b32_e32 v24, v4
	v_mov_b32_e32 v25, v4
	v_mov_b32_e32 v26, v4
	v_mov_b32_e32 v27, v4
	v_mov_b32_e32 v28, v4
	v_mov_b32_e32 v29, v4
	v_mov_b32_e32 v30, v4
	v_mov_b32_e32 v31, v4
	v_mov_b32_e32 v32, v4
	v_mov_b32_e32 v33, v4
	v_mov_b32_e32 v34, v4
	v_mov_b32_e32 v35, v4
	v_mov_b32_e32 v44, v4
	v_mov_b32_e32 v45, v4
	v_mov_b32_e32 v46, v4
	v_mov_b32_e32 v47, v4
	v_mov_b32_e32 v36, v4
	v_mov_b32_e32 v37, v4
	v_mov_b32_e32 v38, v4
	v_mov_b32_e32 v39, v4
	v_mov_b32_e32 v40, v4
	v_mov_b32_e32 v41, v4
	v_mov_b32_e32 v42, v4
	v_mov_b32_e32 v43, v4
	v_mov_b32_e32 v48, v4
	v_mov_b32_e32 v49, v4
	v_mov_b32_e32 v50, v4
	v_mov_b32_e32 v51, v4
	v_mov_b32_e32 v52, v4
	v_mov_b32_e32 v53, v4
	v_mov_b32_e32 v54, v4
	v_mov_b32_e32 v55, v4
	v_mov_b32_e32 v56, v4
	v_mov_b32_e32 v57, v4
	v_mov_b32_e32 v58, v4
	v_mov_b32_e32 v59, v4
	v_mov_b32_e32 v60, v4
	v_mov_b32_e32 v61, v4
	v_mov_b32_e32 v62, v4
	v_mov_b32_e32 v63, v4
	v_mov_b32_e32 v64, v4
	v_mov_b32_e32 v65, v4
	v_mov_b32_e32 v66, v4
	v_mov_b32_e32 v67, v4
	v_readlane_b32 s10, v127, 2
	v_readlane_b32 s11, v127, 3
	v_readfirstlane_b32 s98, v76
	s_movk_i32 s99, 0x6000
	s_add_i32 s101, s98, s99
	s_mov_b32 m0, s101
	s_add_i32 s101, s101, 0x2000
	global_load_lds_dwordx4 v[0:1], off
	s_mov_b32 m0, s101
	s_add_i32 s101, s101, 0x2000
	global_load_lds_dwordx4 v[68:69], off
	s_mov_b32 m0, s101
	s_add_i32 s99, s99, 0x6000
	global_load_lds_dwordx4 v[70:71], off
	s_cmp_eq_u32 s99, 0x12000
	s_cselect_b32 s99, 0, s99
	v_lshl_add_u64 v[0:1], v[0:1], 0, 64
	v_lshl_add_u64 v[68:69], v[68:69], 0, 64
	v_lshl_add_u64 v[70:71], v[70:71], 0, 64
	s_add_i32 s101, s98, s99
	s_mov_b32 m0, s101
	s_add_i32 s101, s101, 0x2000
	global_load_lds_dwordx4 v[0:1], off
	s_mov_b32 m0, s101
	s_add_i32 s101, s101, 0x2000
	global_load_lds_dwordx4 v[68:69], off
	s_mov_b32 m0, s101
	s_add_i32 s99, s99, 0x6000
	global_load_lds_dwordx4 v[70:71], off
	s_cmp_eq_u32 s99, 0x12000
	s_cselect_b32 s99, 0, s99
	v_lshl_add_u64 v[0:1], v[0:1], 0, 64
	v_lshl_add_u64 v[68:69], v[68:69], 0, 64
	v_lshl_add_u64 v[70:71], v[70:71], 0, 64
	s_mov_b32 s100, 0
	s_waitcnt vmcnt(6)
	s_barrier
	v_or_b32_e32 v112, s100, v77
	v_add_u32_e32 v113, v112, v78
	v_add_u32_e32 v112, v112, v79
	ds_read_b128 v[80:83], v113 offset:16384
	ds_read_b128 v[84:87], v113 offset:17408
	ds_read_b128 v[88:91], v113 offset:18432
	ds_read_b128 v[92:95], v113 offset:19456
	ds_read_b128 v[96:99], v112
	ds_read_b128 v[100:103], v112 offset:1024
	ds_read_b128 v[104:107], v112 offset:2048
	ds_read_b128 v[108:111], v112 offset:3072
	s_add_i32 s100, s100, 0x6000
	s_cmp_eq_u32 s100, 0x12000
	s_cselect_b32 s100, 0, s100
; template <int MODE, bool SWAP, int MT>
; DI void gemm_tile(const int wv_, const Params& p, const u16* __restrict__ A, const u16* __restrict__ Bt, int brow, int bcol, char* smem, const float* gnext) {
;     ...
;   for (int t = 0; t < 32; ++t) {
;     asm volatile("s_waitcnt vmcnt(0)" ::: "memory");
;     __syncthreads();
;     if (t + 1 < 32) stage(t + 1, (t + 1) & 1);
;     const char* sA = smem + (t & 1) * 24576; const char* sB = sA + 16384;
;     bf16x8 Af[MT], Bf[4];
; #pragma unroll
;     for (int n = 0; n < 4; ++n) Bf[n] = *(const bf16x8*)(sB + (wc * 64 + n * 16 + fr) * 64 + fq * 16);
;     constexpr int MH = MT >= 2 ? MT / 2 : 1;
; #pragma unroll
;     for (int m = 0; m < MH; ++m) Af[m] = *(const bf16x8*)(sA + (wr * (16 * MT) + m * 16 + fr) * 64 + fq * 16);
;     __builtin_amdgcn_sched_barrier(0);
; #pragma unroll
;     for (int m = MH; m < MT; ++m) Af[m] = *(const bf16x8*)(sA + (wr * (16 * MT) + m * 16 + fr) * 64 + fq * 16);
; #pragma unroll
;     for (int m = 0; m < MH; ++m)
; #pragma unroll
;       for (int n = 0; n < 4; ++n)
;         acc[m][n] = SWAP ? __builtin_amdgcn_mfma_f32_16x16x32_bf16(Bf[n], Af[m], acc[m][n], 0, 0, 0)
;                          : __builtin_amdgcn_mfma_f32_16x16x32_bf16(Af[m], Bf[n], acc[m][n], 0, 0, 0);
;     __builtin_amdgcn_sched_barrier(0);
; #pragma unroll
;     for (int m = MH; m < MT; ++m)
; #pragma unroll
;       for (int n = 0; n < 4; ++n)
;         acc[m][n] = SWAP ? __builtin_amdgcn_mfma_f32_16x16x32_bf16(Bf[n], Af[m], acc[m][n], 0, 0, 0)
;                          : __builtin_amdgcn_mfma_f32_16x16x32_bf16(Af[m], Bf[n], acc[m][n], 0, 0, 0);
.LBB0_373:
	s_add_i32 s6, s1, 1
	s_waitcnt lgkmcnt(0)
	v_mfma_f32_16x16x32_bf16 v[64:67], v[80:83], v[96:99], v[64:67]
	v_mfma_f32_16x16x32_bf16 v[60:63], v[84:87], v[96:99], v[60:63]
	v_mfma_f32_16x16x32_bf16 v[56:59], v[88:91], v[96:99], v[56:59]
	v_mfma_f32_16x16x32_bf16 v[52:55], v[92:95], v[96:99], v[52:55]
	v_mfma_f32_16x16x32_bf16 v[48:51], v[80:83], v[100:103], v[48:51]
	v_mfma_f32_16x16x32_bf16 v[40:43], v[84:87], v[100:103], v[40:43]
	v_mfma_f32_16x16x32_bf16 v[36:39], v[88:91], v[100:103], v[36:39]
	v_mfma_f32_16x16x32_bf16 v[44:47], v[92:95], v[100:103], v[44:47]
	s_cmp_gt_u32 s1, 29
	s_cbranch_scc1 .Lpp_last_3
	s_waitcnt vmcnt(3)
	s_barrier
	s_cmp_gt_u32 s1, 28
	s_cbranch_scc1 .Lpp_nodma_3
	s_add_i32 s101, s98, s99
	s_mov_b32 m0, s101
	s_add_i32 s101, s101, 0x2000
	global_load_lds_dwordx4 v[0:1], off
	s_mov_b32 m0, s101
	s_add_i32 s101, s101, 0x2000
	global_load_lds_dwordx4 v[68:69], off
	s_mov_b32 m0, s101
	s_add_i32 s99, s99, 0x6000
	global_load_lds_dwordx4 v[70:71], off
	s_cmp_eq_u32 s99, 0x12000
	s_cselect_b32 s99, 0, s99
	v_lshl_add_u64 v[0:1], v[0:1], 0, 64
	v_lshl_add_u64 v[68:69], v[68:69], 0, 64
	v_lshl_add_u64 v[70:71], v[70:71], 0, 64
.Lpp_nodma_3:
	v_mfma_f32_16x16x32_bf16 v[32:35], v[80:83], v[104:107], v[32:35]
	v_mfma_f32_16x16x32_bf16 v[28:31], v[84:87], v[104:107], v[28:31]
	v_mfma_f32_16x16x32_bf16 v[24:27], v[88:91], v[104:107], v[24:27]
	v_mfma_f32_16x16x32_bf16 v[20:23], v[92:95], v[104:107], v[20:23]
	v_mfma_f32_16x16x32_bf16 v[16:19], v[80:83], v[108:111], v[16:19]
	v_mfma_f32_16x16x32_bf16 v[12:15], v[84:87], v[108:111], v[12:15]
	v_mfma_f32_16x16x32_bf16 v[8:11], v[88:91], v[108:111], v[8:11]
	v_mfma_f32_16x16x32_bf16 v[4:7], v[92:95], v[108:111], v[4:7]
	v_or_b32_e32 v112, s100, v77
	v_add_u32_e32 v113, v112, v78
	v_add_u32_e32 v112, v112, v79
	ds_read_b128 v[80:83], v113 offset:16384
	ds_read_b128 v[84:87], v113 offset:17408
	ds_read_b128 v[88:91], v113 offset:18432
	ds_read_b128 v[92:95], v113 offset:19456
	ds_read_b128 v[96:99], v112
	ds_read_b128 v[100:103], v112 offset:1024
	ds_read_b128 v[104:107], v112 offset:2048
	ds_read_b128 v[108:111], v112 offset:3072
	s_add_i32 s100, s100, 0x6000
	s_cmp_eq_u32 s100, 0x12000
	s_cselect_b32 s100, 0, s100
	s_mov_b32 s1, s6
	s_branch .LBB0_373
; template <int MODE, bool SWAP, int MT>
; DI void gemm_tile(const int wv_, const Params& p, const u16* __restrict__ A, const u16* __restrict__ Bt, int brow, int bcol, char* smem, const float* gnext) {
;     ...
;   for (int t = 0; t < 32; ++t) {
;     asm volatile("s_waitcnt vmcnt(0)" ::: "memory");
;     __syncthreads();
;     if (t + 1 < 32) stage(t + 1, (t + 1) & 1);
;     const char* sA = smem + (t & 1) * 24576; const char* sB = sA + 16384;
;     bf16x8 Af[MT], Bf[4];
; #pragma unroll
;     for (int n = 0; n < 4; ++n) Bf[n] = *(const bf16x8*)(sB + (wc * 64 + n * 16 + fr) * 64 + fq * 16);
;     constexpr int MH = MT >= 2 ? MT / 2 : 1;
; #pragma unroll
;     for (int m = 0; m < MH; ++m) Af[m] = *(const bf16x8*)(sA + (wr * (16 * MT) + m * 16 + fr) * 64 + fq * 16);
;     __builtin_amdgcn_sched_barrier(0);
; #pragma unroll
;     for (int m = MH; m < MT; ++m) Af[m] = *(const bf16x8*)(sA + (wr * (16 * MT) + m * 16 + fr) * 64 + fq * 16);
; #pragma unroll
;     for (int m = 0; m < MH; ++m)
; #pragma unroll
;       for (int n = 0; n < 4; ++n)
;         acc[m][n] = SWAP ? __builtin_amdgcn_mfma_f32_16x16x32_bf16(Bf[n], Af[m], acc[m][n], 0, 0, 0)
;                          : __builtin_amdgcn_mfma_f32_16x16x32_bf16(Af[m], Bf[n], acc[m][n], 0, 0, 0);
;     __builtin_amdgcn_sched_barrier(0);
; #pragma unroll
;     for (int m = MH; m < MT; ++m)
; #pragma unroll
;       for (int n = 0; n < 4; ++n)
;         acc[m][n] = SWAP ? __builtin_amdgcn_mfma_f32_16x16x32_bf16(Bf[n], Af[m], acc[m][n], 0, 0, 0)
;                          : __builtin_amdgcn_mfma_f32_16x16x32_bf16(Af[m], Bf[n], acc[m][n], 0, 0, 0);
;   }
;   __syncthreads();
;     ...
;         const float rs = rowscale(p.ss, R);
; #pragma unroll
;         for (int n = 0; n < 4; ++n) { acc[m][n][0] *= rs; acc[m][n][1] *= rs; acc[m][n][2] *= rs; acc[m][n][3] *= rs; }
;         if (MODE == 0 && bcol >= 512 && bcol < 1536) {
;           int b = R / P, pos = R - b * P;
;           u16* dstb = (bcol < 1024 ? p.kc : p.vc);
; #pragma unroll
;           for (int n = 0; n < 4; ++n) {
;             int cc = (bcol & 511) + wc * 64 + n * 16 + fq * 4;
;             uint2 o; o.x = pack2(acc[m][n][0], acc[m][n][1]); o.y = pack2(acc[m][n][2], acc[m][n][3]);
;             *(uint2*)(dstb + ((size_t)((b * 8 + (cc >> 6)) * P + pos)) * 64 + (cc & 63)) = o;
;           }
;         } else {
;           const int LD = MODE == 0 ? LD_AB : LD_CD;
.Lpp_last_3:
	v_mfma_f32_16x16x32_bf16 v[32:35], v[80:83], v[104:107], v[32:35]
	v_mfma_f32_16x16x32_bf16 v[28:31], v[84:87], v[104:107], v[28:31]
	v_mfma_f32_16x16x32_bf16 v[24:27], v[88:91], v[104:107], v[24:27]
	v_mfma_f32_16x16x32_bf16 v[20:23], v[92:95], v[104:107], v[20:23]
	v_mfma_f32_16x16x32_bf16 v[16:19], v[80:83], v[108:111], v[16:19]
	v_mfma_f32_16x16x32_bf16 v[12:15], v[84:87], v[108:111], v[12:15]
	v_mfma_f32_16x16x32_bf16 v[8:11], v[88:91], v[108:111], v[8:11]
	v_mfma_f32_16x16x32_bf16 v[4:7], v[92:95], v[108:111], v[4:7]
	s_mov_b32 s1, s6
	v_add_u32_e32 v0, v77, v79
	v_add_u32_e32 v1, v77, v78
	s_waitcnt vmcnt(0)
	s_waitcnt vmcnt(0)
	s_barrier
	ds_read_b128 v[68:71], v0 offset:25600
	ds_read_b128 v[80:83], v0 offset:24576
	ds_read_b128 v[76:79], v1 offset:44032
	ds_read_b128 v[84:87], v1 offset:43008
	ds_read_b128 v[88:91], v1 offset:41984
	ds_read_b128 v[92:95], v1 offset:40960
	s_waitcnt lgkmcnt(0)
	v_mfma_f32_16x16x32_bf16 v[64:67], v[92:95], v[80:83], v[64:67]
	v_mfma_f32_16x16x32_bf16 v[60:63], v[88:91], v[80:83], v[60:63]
	v_mfma_f32_16x16x32_bf16 v[56:59], v[84:87], v[80:83], v[56:59]
	v_mfma_f32_16x16x32_bf16 v[52:55], v[76:79], v[80:83], v[52:55]
	ds_read_b128 v[80:83], v0 offset:26624
	ds_read_b128 v[96:99], v0 offset:27648
	v_mfma_f32_16x16x32_bf16 v[48:51], v[92:95], v[68:71], v[48:51]
	v_mfma_f32_16x16x32_bf16 v[40:43], v[88:91], v[68:71], v[40:43]
	v_mfma_f32_16x16x32_bf16 v[36:39], v[84:87], v[68:71], v[36:39]
	v_mfma_f32_16x16x32_bf16 v[44:47], v[76:79], v[68:71], v[44:47]
	v_or_b32_e32 v0, s0, v75
	v_lshl_add_u32 v68, v74, 6, v0
	v_ashrrev_i32_e32 v69, 31, v68
	v_lshlrev_b64 v[70:71], 6, v[68:69]
	v_lshl_add_u64 v[74:75], s[90:91], 0, v[70:71]
	s_waitcnt lgkmcnt(1)
	v_mfma_f32_16x16x32_bf16 v[32:35], v[92:95], v[80:83], v[32:35]
	s_waitcnt lgkmcnt(0)
	s_barrier
	v_mfma_f32_16x16x32_bf16 v[28:31], v[88:91], v[80:83], v[28:31]
	v_lshlrev_b32_e32 v2, 2, v73
	s_add_i32 s0, s23, 0xfffffe00
	s_cmpk_gt_u32 s0, 0x3ff
	v_mfma_f32_16x16x32_bf16 v[24:27], v[84:87], v[80:83], v[24:27]
	s_cselect_b64 s[8:9], -1, 0
	s_cmpk_lt_u32 s23, 0x400
	s_movk_i32 s0, 0x1058
	v_mfma_f32_16x16x32_bf16 v[20:23], v[76:79], v[80:83], v[20:23]
	s_cselect_b64 s[6:7], -1, 0
	s_mov_b64 s[10:11], -1
	v_mfma_f32_16x16x32_bf16 v[12:15], v[88:91], v[96:99], v[12:15]
	v_mfma_f32_16x16x32_bf16 v[8:11], v[84:87], v[96:99], v[8:11]
	v_mfma_f32_16x16x32_bf16 v[4:7], v[76:79], v[96:99], v[4:7]
	v_lshlrev_b32_e32 v77, 6, v72
	global_load_dwordx4 v[70:73], v[74:75], off offset:32
	global_load_dwordx4 v[78:81], v[74:75], off offset:16
	global_load_dwordx4 v[82:85], v[74:75], off
	global_load_dwordx4 v[86:89], v[74:75], off offset:48
	v_or_b32_e32 v76, s23, v77
	v_mfma_f32_16x16x32_bf16 v[16:19], v[92:95], v[96:99], v[16:19]
	v_or_b32_e32 v0, v76, v2
	v_cmp_gt_i32_e64 s[0:1], s0, v0
	s_waitcnt vmcnt(2)
	v_mov_b32_e32 v90, v79
	s_waitcnt vmcnt(1)
	v_mov_b32_e32 v74, v83
	v_mov_b32_e32 v75, v84
	v_mov_b32_e32 v91, v80
	v_mov_b32_e32 v83, v85
	v_mov_b32_e32 v79, v81
	v_mov_b32_e32 v80, v71
	v_pk_add_f32 v[74:75], v[74:75], v[82:83]
	v_pk_add_f32 v[78:79], v[90:91], v[78:79]
	v_pk_add_f32 v[70:71], v[70:71], v[80:81]
	v_mov_b32_e32 v80, v73
	v_pk_add_f32 v[74:75], v[74:75], v[74:75] op_sel:[0,1] op_sel_hi:[1,0]
	v_pk_add_f32 v[78:79], v[78:79], v[78:79] op_sel:[0,1] op_sel_hi:[1,0]
	v_pk_add_f32 v[72:73], v[72:73], v[80:81]
	s_waitcnt vmcnt(0)
	v_mov_b32_e32 v75, v86
	v_mov_b32_e32 v79, v87
	v_mov_b32_e32 v71, v88
	v_mov_b32_e32 v73, v89
	v_pk_add_f32 v[74:75], v[74:75], v[78:79]
	v_pk_add_f32 v[70:71], v[70:71], v[72:73]
	s_nop 0
	v_pk_add_f32 v[70:71], v[74:75], v[70:71]
	s_nop 0
	v_add_f32_e32 v1, v70, v71
	v_mov_b32_e32 v70, 0x358637bd
	v_fmamk_f32 v1, v1, 0x3a800000, v70
	v_cmp_gt_f32_e32 vcc, s96, v1
	v_mul_f32_e32 v70, 0x4b800000, v1
	s_nop 0
	v_cndmask_b32_e32 v1, v1, v70, vcc
	v_rsq_f32_e32 v1, v1
	s_nop 0
	v_mul_f32_e32 v70, 0x45800000, v1
	v_cndmask_b32_e32 v72, v1, v70, vcc
	v_pk_mul_f32 v[70:71], v[64:65], v[72:73] op_sel_hi:[1,0]
	v_pk_mul_f32 v[66:67], v[66:67], v[72:73] op_sel_hi:[1,0]
	v_pk_mul_f32 v[64:65], v[60:61], v[72:73] op_sel_hi:[1,0]
	v_pk_mul_f32 v[62:63], v[62:63], v[72:73] op_sel_hi:[1,0]
	v_pk_mul_f32 v[60:61], v[56:57], v[72:73] op_sel_hi:[1,0]
	v_pk_mul_f32 v[58:59], v[58:59], v[72:73] op_sel_hi:[1,0]
	v_pk_mul_f32 v[56:57], v[52:53], v[72:73] op_sel_hi:[1,0]
	v_pk_mul_f32 v[52:53], v[54:55], v[72:73] op_sel_hi:[1,0]
	s_and_b64 vcc, exec, s[8:9]
	s_cbranch_vccz .LBB0_388
	v_mov_b64_e32 v[54:55], s[68:69]
	v_mad_i64_i32 v[72:73], s[10:11], v68, s35, v[54:55]
	v_lshlrev_b64 v[54:55], 7, v[68:69]
	s_and_saveexec_b64 s[10:11], s[0:1]
	s_cbranch_execz .LBB0_378
	s_movk_i32 s0, 0x5ff
	v_add_u32_e32 v1, 0xfffffc00, v0
	v_cmp_lt_i32_e32 vcc, s0, v0
	s_movk_i32 s0, 0xa00
	v_cvt_pk_bf16_f32 v74, v70, v71
	v_cndmask_b32_e32 v78, v0, v1, vcc
	v_ashrrev_i32_e32 v79, 31, v78
	v_cvt_pk_bf16_f32 v75, v66, v67
	v_lshl_add_u64 v[78:79], v[78:79], 1, v[72:73]
	v_cmp_eq_u32_e32 vcc, s0, v76
	global_store_dwordx2 v[78:79], v[74:75], off
	s_and_b64 exec, exec, vcc
	s_cbranch_execz .LBB0_378
	v_lshl_add_u64 v[78:79], s[78:79], 0, v[54:55]
	v_mov_b32_e32 v1, v3
	v_lshl_add_u64 v[78:79], v[0:1], 1, v[78:79]
	v_add_co_u32_e32 v78, vcc, 0xfffff000, v78
	s_nop 1
	v_addc_co_u32_e32 v79, vcc, -1, v79, vcc
	global_store_dwordx2 v[78:79], v[74:75], off offset:-1024

; template <int MODE, bool SWAP, int MT>
; DI void gemm_tile(const int wv_, const Params& p, const u16* __restrict__ A, const u16* __restrict__ Bt, int brow, int bcol, char* smem, const float* gnext) {
;     ...
;   const int tid = tid_, wid = tid >> 6, lane = tid & 63, wr = wid >> 1, wc = wid & 1, fr = lane & 15, fq = lane >> 4;
;   f32x4 acc[MT][4];
; #pragma unroll
;   for (int m = 0; m < MT; ++m)
; #pragma unroll
;     for (int n = 0; n < 4; ++n) acc[m][n] = f32x4{0.f, 0.f, 0.f, 0.f};
;   const int ra = tid >> 2, cb = (tid & 3) * 8;
;   const u16* ga0 = A + (size_t)(brow + ra) * 1024 + cb;
;   const u16* ga1 = A + (size_t)(brow + 128 + ra) * 1024 + cb;
;   const u16* gb0 = Bt + (size_t)(bcol + ra) * 1024 + cb;
;   auto stage = [&](int t, int buf) {
;     char* sA = smem + buf * 24576; char* sB = sA + 16384;
;     if (MT >= 2 || tid < 256) __builtin_amdgcn_global_load_lds((const unsigned*)(ga0 + t * 32), (unsigned*)(sA + tid * 16), 16, 0, 0);
;     if (MT == 4) __builtin_amdgcn_global_load_lds((const unsigned*)(ga1 + t * 32), (unsigned*)(sA + 8192 + tid * 16), 16, 0, 0);
;     __builtin_amdgcn_global_load_lds((const unsigned*)(gb0 + t * 32), (unsigned*)(sB + tid * 16), 16, 0, 0);
;   };
;   stage(0, 0);
.LBB0_828:
	s_ashr_i32 s0, s28, 31
	s_mov_b32 s3, 0
	s_lshr_b32 s0, s0, 29
	s_add_i32 s0, s28, s0
	v_mbcnt_lo_u32_b32 v0, -1, s3
	v_mbcnt_hi_u32_b32 v0, -1, v0
	s_ashr_i32 s1, s0, 3
	v_add_u32_e32 v77, s33, v0
	s_lshl_b32 s0, s1, 8
	s_mov_b32 s3, s16
	v_ashrrev_i32_e32 v12, 2, v77
	v_add_u32_e32 v0, s0, v12
	s_mov_b32 s3, s17
	s_waitcnt lgkmcnt(0)
	v_ashrrev_i32_e32 v1, 31, v0
	v_lshlrev_b64 v[4:5], 11, v[0:1]
	v_lshlrev_b32_e32 v74, 4, v77
	v_lshl_add_u64 v[6:7], s[50:51], 0, v[4:5]
	v_and_b32_e32 v2, 48, v74
	v_add_u32_e32 v0, 0x80, v0
	v_readfirstlane_b32 s3, v74
	s_lshl_b32 s2, s1, 10
	s_lshl_b32 s1, s28, 7
	v_lshl_add_u64 v[6:7], v[6:7], 0, v[2:3]
	v_ashrrev_i32_e32 v1, 31, v0
	s_mov_b32 m0, s3
	s_sub_i32 s12, s1, s2
	v_lshlrev_b64 v[8:9], 11, v[0:1]
	global_load_lds_dwordx4 v[6:7], off
	v_add_u32_e32 v6, 0x2000, v74
	v_lshl_add_u64 v[0:1], s[50:51], 0, v[8:9]
	v_add_u32_e32 v10, s12, v12
	v_readfirstlane_b32 s3, v6
	v_lshl_add_u64 v[0:1], v[0:1], 0, v[2:3]
	v_ashrrev_i32_e32 v11, 31, v10
	s_mov_b32 m0, s3
	v_lshlrev_b64 v[10:11], 11, v[10:11]
	global_load_lds_dwordx4 v[0:1], off
	v_add_u32_e32 v0, 0x4000, v74
	v_lshl_add_u64 v[10:11], s[6:7], 0, v[10:11]
	v_readfirstlane_b32 s3, v0
	v_lshl_add_u64 v[10:11], v[10:11], 0, v[2:3]
	s_mov_b32 m0, s3
	v_and_b32_e32 v73, 15, v77
	global_load_lds_dwordx4 v[10:11], off
	v_readlane_b32 s4, v127, 28
	v_bfe_u32 v76, v77, 6, 1
	v_ashrrev_i32_e32 v72, 7, v77
	v_lshlrev_b32_e32 v0, 6, v73
	v_or_b32_e32 v4, v4, v2
	v_readlane_b32 s5, v127, 29
	v_lshl_or_b32 v78, v76, 12, v0
	v_lshl_or_b32 v79, v72, 12, v0
	v_lshl_add_u64 v[0:1], s[4:5], 0, v[4:5]
	v_add_u32_e32 v4, s23, v12
	v_subrev_u32_e32 v4, s2, v4
	v_ashrrev_i32_e32 v5, 31, v4
	v_lshlrev_b64 v[4:5], 11, v[4:5]
	v_readlane_b32 s2, v127, 30
	v_or_b32_e32 v4, v4, v2
	v_readlane_b32 s3, v127, 31
	v_or_b32_e32 v8, v8, v2
	s_mov_b32 s1, 0
	v_lshl_add_u64 v[70:71], s[2:3], 0, v[4:5]
	v_mov_b32_e32 v4, 0
	v_and_b32_e32 v75, 48, v77
	v_lshl_add_u64 v[68:69], s[4:5], 0, v[8:9]
	v_mov_b32_e32 v5, v4
	v_mov_b32_e32 v6, v4
	v_mov_b32_e32 v7, v4
	v_mov_b32_e32 v8, v4
	v_mov_b32_e32 v9, v4
	v_mov_b32_e32 v10, v4
	v_mov_b32_e32 v11, v4
	v_mov_b32_e32 v12, v4
	v_mov_b32_e32 v13, v4
	v_mov_b32_e32 v14, v4
	v_mov_b32_e32 v15, v4
	v_mov_b32_e32 v16, v4
	v_mov_b32_e32 v17, v4
	v_mov_b32_e32 v18, v4
	v_mov_b32_e32 v19, v4
	v_mov_b32_e32 v20, v4
	v_mov_b32_e32 v21, v4
	v_mov_b32_e32 v22, v4
	v_mov_b32_e32 v23, v4
	v_mov_b32_e32 v24, v4
	v_mov_b32_e32 v25, v4
	v_mov_b32_e32 v26, v4
	v_mov_b32_e32 v27, v4
	v_mov_b32_e32 v28, v4
	v_mov_b32_e32 v29, v4
	v_mov_b32_e32 v30, v4
	v_mov_b32_e32 v31, v4
	v_mov_b32_e32 v32, v4
	v_mov_b32_e32 v33, v4
	v_mov_b32_e32 v34, v4
	v_mov_b32_e32 v35, v4
	v_mov_b32_e32 v36, v4
	v_mov_b32_e32 v37, v4
	v_mov_b32_e32 v38, v4
	v_mov_b32_e32 v39, v4
	v_mov_b32_e32 v40, v4
	v_mov_b32_e32 v41, v4
	v_mov_b32_e32 v42, v4
	v_mov_b32_e32 v43, v4
	v_mov_b32_e32 v44, v4
	v_mov_b32_e32 v45, v4
	v_mov_b32_e32 v46, v4
	v_mov_b32_e32 v47, v4
	v_mov_b32_e32 v48, v4
	v_mov_b32_e32 v49, v4
	v_mov_b32_e32 v50, v4
	v_mov_b32_e32 v51, v4
	v_mov_b32_e32 v52, v4
	v_mov_b32_e32 v53, v4
	v_mov_b32_e32 v54, v4
	v_mov_b32_e32 v55, v4
	v_mov_b32_e32 v56, v4
	v_mov_b32_e32 v57, v4
	v_mov_b32_e32 v58, v4
	v_mov_b32_e32 v59, v4
	v_mov_b32_e32 v60, v4
	v_mov_b32_e32 v61, v4
	v_mov_b32_e32 v62, v4
	v_mov_b32_e32 v63, v4
	v_mov_b32_e32 v64, v4
	v_mov_b32_e32 v65, v4
	v_mov_b32_e32 v66, v4
	v_mov_b32_e32 v67, v4
	v_readfirstlane_b32 s98, v74
	s_movk_i32 s99, 0x6000
	s_add_i32 s101, s98, s99
	s_mov_b32 m0, s101
	s_add_i32 s101, s101, 0x2000
	global_load_lds_dwordx4 v[0:1], off
	s_mov_b32 m0, s101
	s_add_i32 s101, s101, 0x2000
	global_load_lds_dwordx4 v[68:69], off
	s_mov_b32 m0, s101
	s_add_i32 s99, s99, 0x6000
	global_load_lds_dwordx4 v[70:71], off
	s_cmp_eq_u32 s99, 0x12000
	s_cselect_b32 s99, 0, s99
	v_lshl_add_u64 v[0:1], v[0:1], 0, 64
	v_lshl_add_u64 v[68:69], v[68:69], 0, 64
	v_lshl_add_u64 v[70:71], v[70:71], 0, 64
	s_add_i32 s101, s98, s99
	s_mov_b32 m0, s101
	s_add_i32 s101, s101, 0x2000
	global_load_lds_dwordx4 v[0:1], off
	s_mov_b32 m0, s101
	s_add_i32 s101, s101, 0x2000
	global_load_lds_dwordx4 v[68:69], off
	s_mov_b32 m0, s101
	s_add_i32 s99, s99, 0x6000
	global_load_lds_dwordx4 v[70:71], off
	s_cmp_eq_u32 s99, 0x12000
	s_cselect_b32 s99, 0, s99
	v_lshl_add_u64 v[0:1], v[0:1], 0, 64
	v_lshl_add_u64 v[68:69], v[68:69], 0, 64
	v_lshl_add_u64 v[70:71], v[70:71], 0, 64
	s_mov_b32 s100, 0
	s_waitcnt vmcnt(6)
	s_barrier
	v_or_b32_e32 v112, s100, v75
	v_add_u32_e32 v113, v112, v78
	v_add_u32_e32 v112, v112, v79
	ds_read_b128 v[80:83], v113 offset:16384
	ds_read_b128 v[84:87], v113 offset:17408
	ds_read_b128 v[88:91], v113 offset:18432
	ds_read_b128 v[92:95], v113 offset:19456
	ds_read_b128 v[96:99], v112
	ds_read_b128 v[100:103], v112 offset:1024
	ds_read_b128 v[104:107], v112 offset:2048
	ds_read_b128 v[108:111], v112 offset:3072
	s_add_i32 s100, s100, 0x6000
	s_cmp_eq_u32 s100, 0x12000
	s_cselect_b32 s100, 0, s100
; template <int MODE, bool SWAP, int MT>
; DI void gemm_tile(const int wv_, const Params& p, const u16* __restrict__ A, const u16* __restrict__ Bt, int brow, int bcol, char* smem, const float* gnext) {
;     ...
;   for (int t = 0; t < 32; ++t) {
;     asm volatile("s_waitcnt vmcnt(0)" ::: "memory");
;     __syncthreads();
;     if (t + 1 < 32) stage(t + 1, (t + 1) & 1);
;     const char* sA = smem + (t & 1) * 24576; const char* sB = sA + 16384;
;     bf16x8 Af[MT], Bf[4];
; #pragma unroll
;     for (int n = 0; n < 4; ++n) Bf[n] = *(const bf16x8*)(sB + (wc * 64 + n * 16 + fr) * 64 + fq * 16);
;     constexpr int MH = MT >= 2 ? MT / 2 : 1;
; #pragma unroll
;     for (int m = 0; m < MH; ++m) Af[m] = *(const bf16x8*)(sA + (wr * (16 * MT) + m * 16 + fr) * 64 + fq * 16);
;     __builtin_amdgcn_sched_barrier(0);
; #pragma unroll
;     for (int m = MH; m < MT; ++m) Af[m] = *(const bf16x8*)(sA + (wr * (16 * MT) + m * 16 + fr) * 64 + fq * 16);
; #pragma unroll
;     for (int m = 0; m < MH; ++m)
; #pragma unroll
;       for (int n = 0; n < 4; ++n)
;         acc[m][n] = SWAP ? __builtin_amdgcn_mfma_f32_16x16x32_bf16(Bf[n], Af[m], acc[m][n], 0, 0, 0)
;                          : __builtin_amdgcn_mfma_f32_16x16x32_bf16(Af[m], Bf[n], acc[m][n], 0, 0, 0);
;     __builtin_amdgcn_sched_barrier(0);
; #pragma unroll
;     for (int m = MH; m < MT; ++m)
; #pragma unroll
;       for (int n = 0; n < 4; ++n)
;         acc[m][n] = SWAP ? __builtin_amdgcn_mfma_f32_16x16x32_bf16(Bf[n], Af[m], acc[m][n], 0, 0, 0)
;                          : __builtin_amdgcn_mfma_f32_16x16x32_bf16(Af[m], Bf[n], acc[m][n], 0, 0, 0);
;   }
;   __syncthreads();
;   if (SWAP) {
; #pragma unroll
;     for (int m = 0; m < MT; ++m) {
;       int R = brow + wr * (16 * MT) + m * 16 + fr;
;       if (MODE == 2) {
;         int b = R / P, pos = R - b * P;
;         const bool valid = pos >= 112;
;         float* hr = valid ? hrow(p, b, pos) : nullptr;
.LBB0_829:
	s_add_i32 s2, s1, 1
	s_waitcnt lgkmcnt(0)
	v_mfma_f32_16x16x32_bf16 v[64:67], v[80:83], v[96:99], v[64:67]
	v_mfma_f32_16x16x32_bf16 v[60:63], v[84:87], v[96:99], v[60:63]
	v_mfma_f32_16x16x32_bf16 v[56:59], v[88:91], v[96:99], v[56:59]
	v_mfma_f32_16x16x32_bf16 v[52:55], v[92:95], v[96:99], v[52:55]
	v_mfma_f32_16x16x32_bf16 v[48:51], v[80:83], v[100:103], v[48:51]
	v_mfma_f32_16x16x32_bf16 v[44:47], v[84:87], v[100:103], v[44:47]
	v_mfma_f32_16x16x32_bf16 v[40:43], v[88:91], v[100:103], v[40:43]
	v_mfma_f32_16x16x32_bf16 v[36:39], v[92:95], v[100:103], v[36:39]
	s_cmp_gt_u32 s1, 29
	s_cbranch_scc1 .Lpp_last_4
	s_waitcnt vmcnt(3)
	s_barrier
	s_cmp_gt_u32 s1, 28
	s_cbranch_scc1 .Lpp_nodma_4
	s_add_i32 s101, s98, s99
	s_mov_b32 m0, s101
	s_add_i32 s101, s101, 0x2000
	global_load_lds_dwordx4 v[0:1], off
	s_mov_b32 m0, s101
	s_add_i32 s101, s101, 0x2000
	global_load_lds_dwordx4 v[68:69], off
	s_mov_b32 m0, s101
	s_add_i32 s99, s99, 0x6000
	global_load_lds_dwordx4 v[70:71], off
	s_cmp_eq_u32 s99, 0x12000
	s_cselect_b32 s99, 0, s99
	v_lshl_add_u64 v[0:1], v[0:1], 0, 64
	v_lshl_add_u64 v[68:69], v[68:69], 0, 64
	v_lshl_add_u64 v[70:71], v[70:71], 0, 64
.Lpp_nodma_4:
	v_mfma_f32_16x16x32_bf16 v[32:35], v[80:83], v[104:107], v[32:35]
	v_mfma_f32_16x16x32_bf16 v[28:31], v[84:87], v[104:107], v[28:31]
	v_mfma_f32_16x16x32_bf16 v[24:27], v[88:91], v[104:107], v[24:27]
	v_mfma_f32_16x16x32_bf16 v[20:23], v[92:95], v[104:107], v[20:23]
	v_mfma_f32_16x16x32_bf16 v[16:19], v[80:83], v[108:111], v[16:19]
	v_mfma_f32_16x16x32_bf16 v[12:15], v[84:87], v[108:111], v[12:15]
	v_mfma_f32_16x16x32_bf16 v[8:11], v[88:91], v[108:111], v[8:11]
	v_mfma_f32_16x16x32_bf16 v[4:7], v[92:95], v[108:111], v[4:7]
	v_or_b32_e32 v112, s100, v75
	v_add_u32_e32 v113, v112, v78
	v_add_u32_e32 v112, v112, v79
	ds_read_b128 v[80:83], v113 offset:16384
	ds_read_b128 v[84:87], v113 offset:17408
	ds_read_b128 v[88:91], v113 offset:18432
	ds_read_b128 v[92:95], v113 offset:19456
	ds_read_b128 v[96:99], v112
	ds_read_b128 v[100:103], v112 offset:1024
	ds_read_b128 v[104:107], v112 offset:2048
	ds_read_b128 v[108:111], v112 offset:3072
	s_add_i32 s100, s100, 0x6000
	s_cmp_eq_u32 s100, 0x12000
	s_cselect_b32 s100, 0, s100
	s_mov_b32 s1, s2
	s_branch .LBB0_829
.Lpp_last_4:
	v_mfma_f32_16x16x32_bf16 v[32:35], v[80:83], v[104:107], v[32:35]
	v_mfma_f32_16x16x32_bf16 v[28:31], v[84:87], v[104:107], v[28:31]
	v_mfma_f32_16x16x32_bf16 v[24:27], v[88:91], v[104:107], v[24:27]
	v_mfma_f32_16x16x32_bf16 v[20:23], v[92:95], v[104:107], v[20:23]
	v_mfma_f32_16x16x32_bf16 v[16:19], v[80:83], v[108:111], v[16:19]
	v_mfma_f32_16x16x32_bf16 v[12:15], v[84:87], v[108:111], v[12:15]
	v_mfma_f32_16x16x32_bf16 v[8:11], v[88:91], v[108:111], v[8:11]
	v_mfma_f32_16x16x32_bf16 v[4:7], v[92:95], v[108:111], v[4:7]
	s_mov_b32 s1, s2
	v_add_u32_e32 v0, v75, v79
	v_add_u32_e32 v1, v75, v78
	s_waitcnt vmcnt(0)
	s_waitcnt vmcnt(0)
	s_barrier
	ds_read_b128 v[80:83], v0 offset:25600
	ds_read_b128 v[84:87], v0 offset:24576
	ds_read_b128 v[88:91], v1 offset:44032
	ds_read_b128 v[92:95], v1 offset:43008
	ds_read_b128 v[96:99], v1 offset:41984
	ds_read_b128 v[100:103], v1 offset:40960
	s_waitcnt lgkmcnt(0)
	v_mfma_f32_16x16x32_bf16 v[68:71], v[100:103], v[84:87], v[64:67]
	v_mfma_f32_16x16x32_bf16 v[60:63], v[96:99], v[84:87], v[60:63]
	v_mfma_f32_16x16x32_bf16 v[56:59], v[92:95], v[84:87], v[56:59]
	v_mfma_f32_16x16x32_bf16 v[52:55], v[88:91], v[84:87], v[52:55]
	ds_read_b128 v[64:67], v0 offset:26624
	ds_read_b128 v[84:87], v0 offset:27648
	v_mfma_f32_16x16x32_bf16 v[48:51], v[100:103], v[80:83], v[48:51]
	v_mfma_f32_16x16x32_bf16 v[44:47], v[96:99], v[80:83], v[44:47]
	v_mfma_f32_16x16x32_bf16 v[40:43], v[92:95], v[80:83], v[40:43]
	v_mfma_f32_16x16x32_bf16 v[36:39], v[88:91], v[80:83], v[36:39]
	v_or_b32_e32 v0, s0, v73
	v_lshl_add_u32 v72, v72, 6, v0
	s_mov_b32 s0, 0x7e07e07f
	v_mul_hi_i32 v0, v72, s0
	s_waitcnt lgkmcnt(1)
	v_mfma_f32_16x16x32_bf16 v[32:35], v[100:103], v[64:67], v[32:35]
	v_lshrrev_b32_e32 v1, 31, v0
	v_ashrrev_i32_e32 v0, 12, v0
	v_add_u32_e32 v0, v0, v1
	v_mfma_f32_16x16x32_bf16 v[28:31], v[96:99], v[64:67], v[28:31]
	s_movk_i32 s0, 0xdf80
	v_mad_i32_i24 v1, v0, s0, v72
	v_cmp_lt_i32_e64 s[2:3], s54, v1
	v_mfma_f32_16x16x32_bf16 v[24:27], v[92:95], v[64:67], v[24:27]
	v_mov_b64_e32 v[74:75], 0
	s_waitcnt lgkmcnt(0)
	s_barrier
	v_mfma_f32_16x16x32_bf16 v[20:23], v[88:91], v[64:67], v[20:23]
	v_mfma_f32_16x16x32_bf16 v[16:19], v[100:103], v[84:87], v[16:19]
	v_mfma_f32_16x16x32_bf16 v[12:15], v[96:99], v[84:87], v[12:15]
	v_mfma_f32_16x16x32_bf16 v[8:11], v[92:95], v[84:87], v[8:11]
	v_mfma_f32_16x16x32_bf16 v[4:7], v[88:91], v[84:87], v[4:7]
	s_and_saveexec_b64 s[0:1], s[2:3]
	s_cbranch_execz .LBB0_832
	s_movk_i32 s4, 0x7f
	v_cmp_lt_u32_e32 vcc, s4, v1
	v_mov_b32_e32 v64, 0xffffff90
	v_mov_b32_e32 v65, 0xffffff80
	v_cndmask_b32_e64 v2, 4, 13, vcc
	v_cndmask_b32_e32 v66, v64, v65, vcc
	v_lshlrev_b32_e32 v0, v2, v0
	v_mov_b32_e32 v64, s85
	v_mov_b32_e32 v65, s43
	v_add3_u32 v0, v66, v1, v0
	v_cndmask_b32_e32 v65, v64, v65, vcc
	v_mov_b32_e32 v64, s84
	v_mov_b32_e32 v67, s42
	v_ashrrev_i32_e32 v1, 31, v0
	v_cndmask_b32_e32 v64, v64, v67, vcc
	v_lshlrev_b64 v[0:1], 12, v[0:1]
	v_lshl_add_u64 v[74:75], v[64:65], 0, v[0:1]
